# plus: norm-phase K-split partial reads batched; R2 units mapped to the XCD that wrote their carried states
# speedup vs baseline: 1.0298x; 1.0026x over previous
; __device__ __forceinline__ void r2_phase(KP p, LAS unsigned char* lds, int G, int bid, int wv) {
;     ...
;     const int tid = tid_, wid = tid >> 6, lane = tid & 63, fr = lane & 15, fq = lane >> 4;
;     unsigned char* ws = p->ws;
;     const bf16_t* qn = (const bf16_t*)(ws + WS_Q); const bf16_t* kn = (const bf16_t*)(ws + WS_K); const bf16_t* vT = (const bf16_t*)(ws + WS_VT);
;     const bf16_t* ST = (const bf16_t*)(ws + WS_ST); const bf16_t* pr = (const bf16_t*)(ws + WS_PR); bf16_t* Y = (bf16_t*)(ws + WS_Y);
;     LAS unsigned char* Ks = lds; LAS unsigned char* Vs = lds + 34816; LAS unsigned char* Pw = lds + 69632 + wid * 4352;
;     for (int u = bid; u < 512; u += G) {
;         const int bh = u >> 4, n = u & 15, b = bh >> 3, h = bh & 7;
;         const size_t row0 = (size_t)b * SEQ + n * 128;
;         float lf = log2_gamma(p->in[18][h]), lb = log2_gamma(p->in[19][h]);
;         asm volatile("" : "+v"(lf), "+v"(lb));
;         {
;             u32x4 kq[4], vq[4];
; #pragma unroll
;             for (int q = 0; q < 4; ++q) { const int c = tid + 512 * q, r = c >> 4, c16 = c & 15;
;                 kq[q] = *(const u32x4*)(kn + (row0 + r) * 1024 + h * 128 + c16 * 8);
;                 vq[q] = *(const u32x4*)(vT + ((size_t)(bh * 18 + 2 + n) * 128 + r) * 128 + c16 * 8); }
; #pragma unroll
;             for (int q = 0; q < 4; ++q) { const int c = tid + 512 * q, r = c >> 4, c16 = c & 15;
;                 *(LAS u32x4*)(Ks + r * 272 + c16 * 16) = kq[q]; *(LAS u32x4*)(Vs + r * 272 + c16 * 16) = vq[q]; }
;         }
;         bf16x8 qf[4];
; #pragma unroll
;         for (int ks = 0; ks < 4; ++ks) qf[ks] = *(const bf16x8*)(qn + (row0 + 16 * wid + fr) * 1024 + h * 128 + 32 * ks + 8 * fq);
;         __syncthreads();
;         f32x4 sc[8];
; #pragma unroll
;         for (int i = 0; i < 8; ++i) sc[i] = (f32x4){0.f, 0.f, 0.f, 0.f};
; #pragma unroll
;         for (int ks = 0; ks < 4; ++ks)
; #pragma unroll
;             for (int i = 0; i < 8; ++i) {
;                 const bf16x8 kf = *(const LAS bf16x8*)(Ks + (16 * i + fr) * 272 + (32 * ks + 8 * fq) * 2);
;                 sc[i] = __builtin_amdgcn_mfma_f32_16x16x32_bf16(qf[ks], kf, sc[i], 0, 0, 0);
;             }
; #pragma unroll
;         for (int i = 0; i < 8; ++i)
; #pragma unroll
;             for (int j = 0; j < 4; ++j) {
;                 const int diff = (16 * wid + 4 * fq + j) - (16 * i + fr);
.LBB0_104:
	s_andn2_b64 vcc, exec, s[0:1]
	s_cbranch_vccnz .LBB0_109
	v_readlane_b32 s0, v253, 4
	v_readlane_b32 s1, v253, 5
	s_waitcnt vmcnt(0)
	v_mov_b32_e32 v9, v221
	s_andn2_b64 vcc, exec, s[0:1]
	s_cbranch_vccnz .LBB0_109
	v_and_b32_e32 v14, 64, v220
	v_xor_b32_e32 v13, 1, v220
	v_add_u32_e32 v14, 64, v14
	v_cmp_lt_i32_e32 vcc, v13, v14
	v_ashrrev_i32_e32 v4, 6, v9
	s_movk_i32 s0, 0x1100
	v_cndmask_b32_e32 v13, v220, v13, vcc
	v_lshlrev_b32_e32 v98, 2, v13
	v_xor_b32_e32 v13, 2, v220
	v_cmp_lt_i32_e32 vcc, v13, v14
	v_mul_lo_u32 v0, v4, s0
	v_readlane_b32 s0, v253, 34
	v_cndmask_b32_e32 v13, v220, v13, vcc
	v_lshlrev_b32_e32 v99, 2, v13
	v_xor_b32_e32 v13, 4, v220
	v_cmp_lt_i32_e32 vcc, v13, v14
	v_add_u32_e32 v10, s0, v0
	v_lshlrev_b32_e32 v0, 4, v9
	v_cndmask_b32_e32 v13, v220, v13, vcc
	v_lshlrev_b32_e32 v100, 2, v13
	v_xor_b32_e32 v13, 8, v220
	v_and_b32_e32 v0, 0xf0, v0
	v_cmp_lt_i32_e32 vcc, v13, v14
	v_bfe_u32 v12, v9, 4, 2
	v_lshl_add_u64 v[2:3], s[80:81], 0, v[0:1]
	s_mov_b64 s[0:1], 0x20eb4000
	v_cndmask_b32_e32 v13, v220, v13, vcc
	v_lshl_add_u64 v[64:65], v[2:3], 0, s[0:1]
	v_writelane_b32 v254, s10, 37
	v_add_u32_e32 v5, 0, v0
	v_lshlrev_b32_e32 v2, 2, v12
	v_lshl_add_u64 v[68:69], s[10:11], 0, v[0:1]
	v_lshlrev_b32_e32 v0, 4, v4
	v_lshlrev_b32_e32 v101, 2, v13
	v_add_u32_e32 v13, 0x200, v9
	v_and_b32_e32 v11, 15, v9
	v_writelane_b32 v254, s11, 38
	v_or_b32_e32 v56, v2, v0
	s_movk_i32 s0, 0x110
	v_ashrrev_i32_e32 v62, 4, v9
	v_ashrrev_i32_e32 v66, 4, v13
	v_add_u32_e32 v13, 0x400, v9
	v_add_u32_e32 v9, 0x600, v9
	v_ashrrev_i32_e32 v55, 31, v0
	v_or_b32_e32 v54, v0, v11
	v_mul_u32_u24_e32 v8, 0x110, v11
	v_mad_u32_u24 v6, v11, s0, v10
	v_lshlrev_b32_e32 v2, 7, v11
	v_lshlrev_b32_e32 v0, 1, v11
	v_writelane_b32 v254, s26, 35
	v_ashrrev_i32_e32 v70, 4, v13
	v_ashrrev_i32_e32 v74, 4, v9
	v_or_b32_e32 v14, 16, v11
	v_or_b32_e32 v16, 32, v11
	v_or_b32_e32 v18, 48, v11
	v_or_b32_e32 v19, 64, v11
	v_or_b32_e32 v20, 0x50, v11
	v_or_b32_e32 v21, 0x60, v11
	v_or_b32_e32 v22, 0x70, v11
	v_sub_u32_e32 v11, v56, v11
	v_writelane_b32 v254, s27, 36
	v_readlane_b32 s4, v253, 63
	v_mul_lo_u32 v9, v62, s0
	v_mul_lo_u32 v13, v66, s0
	v_mul_lo_u32 v15, v70, s0
	v_mul_lo_u32 v17, v74, s0
	v_cmp_lt_i32_e64 s[0:1], -1, v11
	v_readlane_b32 s5, v254, 0
	v_lshl_add_u64 v[72:73], s[26:27], 0, v[0:1]
	v_writelane_b32 v254, s0, 19
	v_lshl_add_u64 v[76:77], s[4:5], 0, v[0:1]
	v_add_u32_e32 v23, v10, v0
	v_writelane_b32 v254, s1, 20
	v_cmp_gt_i32_e64 s[0:1], 1, v11
	v_sub_u32_e32 v0, 0, v11
	v_cvt_f32_u32_e32 v219, v0
	v_writelane_b32 v254, s0, 17
	v_add_u32_e32 v0, 1, v11
	v_cvt_f32_u32_e32 v215, v0
	v_writelane_b32 v254, s1, 18
	v_cmp_lt_i32_e64 s[0:1], -2, v11
	v_not_b32_e32 v0, v11
	v_cvt_f32_u32_e32 v218, v0
	v_writelane_b32 v254, s0, 15
	v_add_u32_e32 v0, 2, v11
	v_cvt_f32_u32_e32 v106, v0
	v_writelane_b32 v254, s1, 16
	v_cmp_gt_i32_e64 s[0:1], 0, v11
	v_sub_u32_e32 v0, -2, v11
	v_cvt_f32_u32_e32 v107, v0
	v_writelane_b32 v254, s0, 13
	v_add_u32_e32 v0, 3, v11
	v_cvt_f32_u32_e32 v108, v0
	v_writelane_b32 v254, s1, 14
	v_cmp_lt_i32_e64 s[0:1], -3, v11
	v_sub_u32_e32 v0, -3, v11
	v_cvt_f32_u32_e32 v109, v0
	v_writelane_b32 v254, s0, 11
	v_sub_u32_e32 v0, v56, v14
	v_lshlrev_b32_e32 v4, 3, v12
	v_writelane_b32 v254, s1, 12
	v_cmp_gt_i32_e64 s[0:1], -1, v11
	v_lshlrev_b32_e32 v3, 4, v12
	v_mul_u32_u24_e32 v24, 0x440, v12
	v_writelane_b32 v254, s0, 9
	v_sub_u32_e32 v12, 0, v0
	v_cvt_f32_u32_e32 v111, v12
	v_writelane_b32 v254, s1, 10
	v_cmp_lt_i32_e64 s[0:1], -4, v11
	v_add_u32_e32 v12, 1, v0
	v_cvt_f32_u32_e32 v112, v12
	v_writelane_b32 v254, s0, 7
	v_not_b32_e32 v12, v0
	v_cvt_f32_u32_e32 v113, v12
	v_writelane_b32 v254, s1, 8
	v_cmp_gt_i32_e64 s[0:1], -2, v11
	v_add_u32_e32 v12, 2, v0
	v_cvt_f32_u32_e32 v114, v12
	v_writelane_b32 v254, s0, 5
	v_sub_u32_e32 v12, -2, v0
	v_cvt_f32_u32_e32 v110, v0
	v_writelane_b32 v254, s1, 6
	v_cmp_lt_i32_e64 s[0:1], -1, v0
	v_cvt_f32_u32_e32 v115, v12
	v_add_u32_e32 v12, 3, v0
	v_writelane_b32 v254, s0, 3
	v_cvt_f32_u32_e32 v116, v12
	v_cvt_f32_u32_e32 v252, v11
	v_writelane_b32 v254, s1, 4
	v_cmp_gt_i32_e64 s[0:1], 1, v0
	v_lshl_add_u32 v11, v14, 1, v10
	v_lshl_add_u32 v25, v16, 1, v10
	v_writelane_b32 v254, s0, 1
	v_lshl_add_u32 v26, v18, 1, v10
	v_lshl_add_u32 v27, v20, 1, v10
	v_writelane_b32 v254, s1, 2
	v_cmp_lt_i32_e64 s[0:1], -2, v0
	v_lshl_add_u32 v28, v22, 1, v10
	s_add_u32 s2, s80, 0x1feb4000
	v_writelane_b32 v254, s0, 21
	v_add_u32_e32 v7, 0, v3
	v_or_b32_e32 v14, 0x1800, v2
	v_writelane_b32 v254, s1, 22
	v_cmp_gt_i32_e64 s[0:1], 0, v0
	s_addc_u32 s3, s81, 0
	v_mov_b32_e32 v57, v55
	v_writelane_b32 v254, s0, 25
	v_ashrrev_i32_e32 v63, 31, v62
	v_ashrrev_i32_e32 v67, 31, v66
	v_writelane_b32 v254, s1, 26
	v_cmp_lt_i32_e64 s[0:1], -3, v0
	v_ashrrev_i32_e32 v71, 31, v70
	v_ashrrev_i32_e32 v75, 31, v74
	v_writelane_b32 v254, s0, 31
	s_mov_b32 s15, 0x3f2aaaab
	v_add_u32_e32 v193, v5, v9
	v_writelane_b32 v254, s1, 32
	v_cmp_gt_i32_e64 s[0:1], -1, v0
	v_add_u32_e32 v194, v5, v13
	v_add_u32_e32 v195, v5, v15
	v_writelane_b32 v254, s0, 29
	v_add_u32_e32 v196, v5, v17
	v_add_u32_e32 v197, v7, v8
	v_writelane_b32 v254, s1, 30
	v_cmp_lt_i32_e64 s[0:1], -4, v0
	v_add_u32_e32 v198, v23, v24
	v_add_u32_e32 v199, v11, v24
	v_writelane_b32 v254, s0, 27
	v_add_u32_e32 v200, v25, v24
	v_add_u32_e32 v201, v26, v24
	v_writelane_b32 v254, s1, 28
	v_cmp_gt_i32_e64 s[0:1], -2, v0
	v_sub_u32_e32 v0, -3, v0
	v_cvt_f32_u32_e32 v117, v0
	v_writelane_b32 v254, s0, 33
	v_sub_u32_e32 v0, v56, v16
	v_sub_u32_e32 v12, 0, v0
	v_writelane_b32 v254, s1, 34
	v_cmp_lt_i32_e64 s[0:1], -1, v0
	v_cvt_f32_u32_e32 v119, v12
	v_add_u32_e32 v12, 1, v0
; #define LAS __attribute__((address_space(3)))
; __device__ __forceinline__ bf16_t f2bf(float x) { return (bf16_t)(cvt_pk_bf16(x, 0.f) & 0xffffu); }
; __device__ __forceinline__ void r2_phase(KP p, LAS unsigned char* lds, int G, int bid, int wv) {
;     ...
;         for (int i = 0; i < 8; ++i)
; #pragma unroll
;             for (int j = 0; j < 4; ++j) {
;                 const int diff = (16 * wid + 4 * fq + j) - (16 * i + fr);
;                 const float df = diff >= 0 ? __builtin_amdgcn_exp2f(lf * (float)diff) : 0.f;
;                 const float db = diff <= 0 ? __builtin_amdgcn_exp2f(lb * (float)(-diff)) : 0.f;
;                 *(LAS bf16_t*)(Pw + (4 * fq + j) * 272 + (16 * i + fr) * 2) = f2bf(sc[i][j] * (df + db));
	v_writelane_b32 v254, s0, 23
	v_cvt_f32_u32_e32 v120, v12
	v_not_b32_e32 v12, v0
	v_writelane_b32 v254, s1, 24
	v_cmp_gt_i32_e64 s[0:1], 1, v0
	v_cvt_f32_u32_e32 v121, v12
	v_add_u32_e32 v12, 2, v0
	v_writelane_b32 v254, s0, 39
	v_cvt_f32_u32_e32 v122, v12
	v_sub_u32_e32 v12, -2, v0
	v_writelane_b32 v254, s1, 40
	v_cmp_lt_i32_e64 s[0:1], -2, v0
	v_cvt_f32_u32_e32 v118, v0
	v_cvt_f32_u32_e32 v123, v12
	v_writelane_b32 v254, s0, 41
	v_add_u32_e32 v12, 3, v0
	v_cvt_f32_u32_e32 v124, v12
	v_writelane_b32 v254, s1, 42
	v_cmp_gt_i32_e64 s[0:1], 0, v0
	v_or_b32_e32 v16, 0x2000, v2
	v_add_u32_e32 v203, v27, v24
	v_writelane_b32 v254, s0, 43
	v_add_u32_e32 v205, v28, v24
	v_add_u32_e32 v206, v6, v3
	v_writelane_b32 v254, s1, 44
	v_cmp_lt_i32_e64 s[0:1], -3, v0
	v_lshlrev_b32_e32 v78, 1, v2
	v_lshlrev_b32_e32 v84, 1, v14
	v_writelane_b32 v254, s0, 45
	v_lshlrev_b32_e32 v86, 1, v16
	s_mov_b32 s12, 0xbfb8aa3b
	v_writelane_b32 v254, s1, 46
	v_cmp_gt_i32_e64 s[0:1], -1, v0
	s_mov_b32 s13, 0xc2b17218
	s_mov_b32 s14, 0x7f800000
	v_writelane_b32 v254, s0, 47
	s_mov_b32 s51, 0x3f317218
	s_mov_b32 s86, 0x33800000
	v_writelane_b32 v254, s1, 48
	v_cmp_lt_i32_e64 s[0:1], -4, v0
	s_mov_b32 s77, 0xf800000
	s_nop 0
	v_writelane_b32 v254, s0, 49
	s_nop 1
	v_writelane_b32 v254, s1, 50
	v_cmp_gt_i32_e64 s[0:1], -2, v0
	v_sub_u32_e32 v0, -3, v0
	v_cvt_f32_u32_e32 v125, v0
	v_writelane_b32 v254, s0, 51
	v_sub_u32_e32 v0, v56, v18
	v_sub_u32_e32 v12, 0, v0
	v_writelane_b32 v254, s1, 52
	v_cmp_lt_i32_e64 s[0:1], -1, v0
	v_cvt_f32_u32_e32 v127, v12
	v_add_u32_e32 v12, 1, v0
	v_writelane_b32 v254, s0, 53
	v_cvt_f32_u32_e32 v128, v12
	v_not_b32_e32 v12, v0
	v_writelane_b32 v254, s1, 54
	v_cmp_gt_i32_e64 s[0:1], 1, v0
	v_cvt_f32_u32_e32 v129, v12
	v_add_u32_e32 v12, 2, v0
	v_writelane_b32 v254, s0, 55
	v_cvt_f32_u32_e32 v130, v12
	v_sub_u32_e32 v12, -2, v0
	v_writelane_b32 v254, s1, 56
	v_cmp_lt_i32_e64 s[0:1], -2, v0
	v_cvt_f32_u32_e32 v126, v0
	v_cvt_f32_u32_e32 v131, v12
	v_writelane_b32 v254, s0, 57
	v_add_u32_e32 v12, 3, v0
	v_cvt_f32_u32_e32 v132, v12
	v_writelane_b32 v254, s1, 58
	v_cmp_gt_i32_e64 s[0:1], 0, v0
	v_or_b32_e32 v18, 0x2800, v2
	v_lshlrev_b32_e32 v88, 1, v18
	v_writelane_b32 v254, s0, 59
	s_nop 1
	v_writelane_b32 v254, s1, 60
	v_cmp_lt_i32_e64 s[0:1], -3, v0
	s_nop 1
	v_writelane_b32 v254, s0, 61
	s_nop 1
	v_writelane_b32 v254, s1, 62
	v_cmp_gt_i32_e64 s[0:1], -1, v0
	s_nop 1
	v_writelane_b32 v254, s0, 63
	s_nop 1
	v_writelane_b32 v255, s1, 0
	v_cmp_lt_i32_e64 s[0:1], -4, v0
	s_nop 1
	v_writelane_b32 v255, s0, 1
	s_nop 1
	v_writelane_b32 v255, s1, 2
	v_cmp_gt_i32_e64 s[0:1], -2, v0
	v_sub_u32_e32 v0, -3, v0
	v_cvt_f32_u32_e32 v133, v0
	v_writelane_b32 v255, s0, 3
	v_sub_u32_e32 v0, v56, v19
	v_sub_u32_e32 v12, 0, v0
	v_writelane_b32 v255, s1, 4
	v_cmp_lt_i32_e64 s[0:1], -1, v0
	v_cvt_f32_u32_e32 v135, v12
	v_add_u32_e32 v12, 1, v0
	v_writelane_b32 v255, s0, 5
	v_cvt_f32_u32_e32 v136, v12
	v_not_b32_e32 v12, v0
	v_writelane_b32 v255, s1, 6
	v_cmp_gt_i32_e64 s[0:1], 1, v0
	v_cvt_f32_u32_e32 v137, v12
	v_add_u32_e32 v12, 2, v0
	v_writelane_b32 v255, s0, 7
	v_cvt_f32_u32_e32 v138, v12
	v_sub_u32_e32 v12, -2, v0
	v_writelane_b32 v255, s1, 8
	v_cmp_lt_i32_e64 s[0:1], -2, v0
	v_cvt_f32_u32_e32 v134, v0
	v_cvt_f32_u32_e32 v139, v12
	v_writelane_b32 v255, s0, 9
	v_add_u32_e32 v12, 3, v0
	v_cvt_f32_u32_e32 v140, v12
	v_writelane_b32 v255, s1, 10
	v_cmp_gt_i32_e64 s[0:1], 0, v0
	v_lshl_add_u32 v19, v19, 1, v10
	v_add_u32_e32 v202, v19, v24
	v_writelane_b32 v255, s0, 11
	s_nop 1
	v_writelane_b32 v255, s1, 12
	v_cmp_lt_i32_e64 s[0:1], -3, v0
	s_nop 1
	v_writelane_b32 v255, s0, 13
	s_nop 1
	v_writelane_b32 v255, s1, 14
	v_cmp_gt_i32_e64 s[0:1], -1, v0
	s_nop 1
	v_writelane_b32 v255, s0, 15
	s_nop 1
	v_writelane_b32 v255, s1, 16
	v_cmp_lt_i32_e64 s[0:1], -4, v0
	s_nop 1
	v_writelane_b32 v255, s0, 17
	s_nop 1
	v_writelane_b32 v255, s1, 18
	v_cmp_gt_i32_e64 s[0:1], -2, v0
	v_sub_u32_e32 v0, -3, v0
	v_cvt_f32_u32_e32 v141, v0
	v_writelane_b32 v255, s0, 19
	v_sub_u32_e32 v0, v56, v20
	v_sub_u32_e32 v12, 0, v0
	v_writelane_b32 v255, s1, 20
	v_cmp_lt_i32_e64 s[0:1], -1, v0
	v_cvt_f32_u32_e32 v143, v12
	v_add_u32_e32 v12, 1, v0
	v_writelane_b32 v255, s0, 21
	v_cvt_f32_u32_e32 v144, v12
	v_not_b32_e32 v12, v0
	v_writelane_b32 v255, s1, 22
	v_cmp_gt_i32_e64 s[0:1], 1, v0
	v_cvt_f32_u32_e32 v145, v12
	v_add_u32_e32 v12, 2, v0
	v_writelane_b32 v255, s0, 23
	v_cvt_f32_u32_e32 v146, v12
	v_sub_u32_e32 v12, -2, v0
	v_writelane_b32 v255, s1, 24
	v_cmp_lt_i32_e64 s[0:1], -2, v0
	v_cvt_f32_u32_e32 v142, v0
	v_cvt_f32_u32_e32 v147, v12
	v_writelane_b32 v255, s0, 25
	v_add_u32_e32 v12, 3, v0
	v_cvt_f32_u32_e32 v148, v12
	v_writelane_b32 v255, s1, 26
	v_cmp_gt_i32_e64 s[0:1], 0, v0
	v_or_b32_e32 v20, 0x3000, v2
	v_lshlrev_b32_e32 v90, 1, v20
	v_writelane_b32 v255, s0, 27
	s_nop 1
	v_writelane_b32 v255, s1, 28
	v_cmp_lt_i32_e64 s[0:1], -3, v0
	s_nop 1
	v_writelane_b32 v255, s0, 29
	s_nop 1
	v_writelane_b32 v255, s1, 30
	v_cmp_gt_i32_e64 s[0:1], -1, v0
	s_nop 1
	v_writelane_b32 v255, s0, 31
	s_nop 1
	v_writelane_b32 v255, s1, 32
	v_cmp_lt_i32_e64 s[0:1], -4, v0
	s_nop 1
	v_writelane_b32 v255, s0, 33
	s_nop 1
	v_writelane_b32 v255, s1, 34
	v_cmp_gt_i32_e64 s[0:1], -2, v0
	v_sub_u32_e32 v0, -3, v0
	v_cvt_f32_u32_e32 v149, v0
	v_writelane_b32 v255, s0, 35
	v_sub_u32_e32 v0, v56, v21
	v_sub_u32_e32 v12, 0, v0
	v_writelane_b32 v255, s1, 36
	v_cmp_lt_i32_e64 s[0:1], -1, v0
	v_cvt_f32_u32_e32 v151, v12
	v_add_u32_e32 v12, 1, v0
	v_writelane_b32 v255, s0, 37
	v_cvt_f32_u32_e32 v152, v12
	v_not_b32_e32 v12, v0
	v_writelane_b32 v255, s1, 38
	v_cmp_gt_i32_e64 s[0:1], 1, v0
	v_cvt_f32_u32_e32 v153, v12
; #define LAS __attribute__((address_space(3)))
; __device__ __forceinline__ bf16_t f2bf(float x) { return (bf16_t)(cvt_pk_bf16(x, 0.f) & 0xffffu); }
; __device__ __forceinline__ float log2_gamma(float logit) { return -log1pf(expf(-logit)) * 1.4426950408889634f; }
; __device__ __forceinline__ void r2_phase(KP p, LAS unsigned char* lds, int G, int bid, int wv) {
;     ...
;     for (int u = bid; u < 512; u += G) {
;         const int bh = u >> 4, n = u & 15, b = bh >> 3, h = bh & 7;
;         const size_t row0 = (size_t)b * SEQ + n * 128;
;         float lf = log2_gamma(p->in[18][h]), lb = log2_gamma(p->in[19][h]);
;         asm volatile("" : "+v"(lf), "+v"(lb));
;     ...
;         for (int i = 0; i < 8; ++i)
; #pragma unroll
;             for (int j = 0; j < 4; ++j) {
;                 const int diff = (16 * wid + 4 * fq + j) - (16 * i + fr);
;                 const float df = diff >= 0 ? __builtin_amdgcn_exp2f(lf * (float)diff) : 0.f;
;                 const float db = diff <= 0 ? __builtin_amdgcn_exp2f(lb * (float)(-diff)) : 0.f;
;                 *(LAS bf16_t*)(Pw + (4 * fq + j) * 272 + (16 * i + fr) * 2) = f2bf(sc[i][j] * (df + db));
;             }
;         __syncthreads();
;         bf16x8 pf[4];
; #pragma unroll
;         for (int ks = 0; ks < 4; ++ks) pf[ks] = *(const LAS bf16x8*)(Pw + fr * 272 + (32 * ks + 8 * fq) * 2);
;         f32x4 o[8];
; #pragma unroll
;         for (int i = 0; i < 8; ++i) o[i] = (f32x4){0.f, 0.f, 0.f, 0.f};
; #pragma unroll
;         for (int ks = 0; ks < 4; ++ks)
; #pragma unroll
;             for (int i = 0; i < 8; ++i) {
;                 const bf16x8 vf = *(const LAS bf16x8*)(Vs + (16 * i + fr) * 272 + (32 * ks + 8 * fq) * 2);
;                 o[i] = __builtin_amdgcn_mfma_f32_16x16x32_bf16(pf[ks], vf, o[i], 0, 0, 0);
;             }
;         const bf16_t* Sf = ST + ((size_t)(bh * 2 + 0) * 16 + n) * 16384; const bf16_t* Sb = ST + ((size_t)(bh * 2 + 1) * 16 + n) * 16384;
;         float sfac[4], sbac[4];
; #pragma unroll
;         for (int j = 0; j < 4; ++j) { const int c = 16 * wid + 4 * fq + j; sfac[j] = __builtin_amdgcn_exp2f(lf * (float)(c + 1)); sbac[j] = __builtin_amdgcn_exp2f(lb * (float)(128 - c)); }
	v_add_u32_e32 v12, 2, v0
	v_writelane_b32 v255, s0, 39
	v_cvt_f32_u32_e32 v154, v12
	v_sub_u32_e32 v12, -2, v0
	v_writelane_b32 v255, s1, 40
	v_cmp_lt_i32_e64 s[0:1], -2, v0
	v_cvt_f32_u32_e32 v150, v0
	v_cmp_lt_i32_e64 s[6:7], -3, v0
	v_writelane_b32 v255, s0, 41
	v_cmp_gt_i32_e64 s[54:55], -1, v0
	v_cvt_f32_u32_e32 v155, v12
	v_writelane_b32 v255, s1, 42
	v_cmp_gt_i32_e64 s[0:1], 0, v0
	v_add_u32_e32 v12, 3, v0
	v_cmp_lt_i32_e64 s[64:65], -4, v0
	v_cmp_gt_i32_e64 s[20:21], -2, v0
	v_sub_u32_e32 v0, -3, v0
	v_cvt_f32_u32_e32 v157, v0
	v_sub_u32_e32 v0, v56, v22
	v_lshl_add_u32 v21, v21, 1, v10
	v_sub_u32_e32 v10, 0, v0
	v_cvt_f32_u32_e32 v159, v10
	v_add_u32_e32 v10, 1, v0
	v_cvt_f32_u32_e32 v160, v10
	v_not_b32_e32 v10, v0
	v_cvt_f32_u32_e32 v161, v10
	v_add_u32_e32 v10, 2, v0
	v_cvt_f32_u32_e32 v163, v10
	v_sub_u32_e32 v10, -2, v0
	v_cmp_lt_i32_e64 s[22:23], -1, v0
	v_cvt_f32_u32_e32 v158, v0
	v_cmp_gt_i32_e64 s[24:25], 1, v0
	v_cmp_lt_i32_e64 s[26:27], -2, v0
	v_cmp_gt_i32_e64 s[28:29], 0, v0
	v_cmp_lt_i32_e64 s[30:31], -3, v0
	v_cmp_gt_i32_e64 s[34:35], -1, v0
	v_cvt_f32_u32_e32 v178, v10
	v_add_u32_e32 v10, 3, v0
	v_cmp_lt_i32_e64 s[36:37], -4, v0
	v_cmp_gt_i32_e64 s[38:39], -2, v0
	v_sub_u32_e32 v0, -3, v0
	v_cvt_f32_u32_e32 v182, v10
	v_cvt_f32_u32_e32 v184, v0
	v_or_b32_e32 v0, 1, v56
	v_sub_u32_e32 v10, 0x80, v56
	v_cvt_f32_i32_e32 v185, v0
	v_cvt_f32_i32_e32 v186, v10
	v_or_b32_e32 v10, 2, v56
	v_sub_u32_e32 v0, 0x80, v0
	v_cvt_f32_i32_e32 v187, v10
	v_cvt_f32_i32_e32 v188, v0
	v_or_b32_e32 v0, 3, v56
	v_sub_u32_e32 v10, 0x80, v10
	v_cvt_f32_i32_e32 v189, v0
	v_cvt_f32_i32_e32 v190, v10
	v_add_u32_e32 v10, 4, v56
	v_sub_u32_e32 v0, 0x80, v0
	v_cvt_f32_u32_e32 v156, v12
	v_cvt_f32_i32_e32 v191, v10
	v_cvt_f32_i32_e32 v192, v0
	v_writelane_b32 v255, s0, 43
	v_or_b32_e32 v10, 0x800, v2
	v_or_b32_e32 v12, 0x1000, v2
	v_or_b32_e32 v22, 0x3800, v2
	v_writelane_b32 v255, s1, 44
	v_lshlrev_b32_e32 v0, 1, v4
	v_add_u32_e32 v204, v21, v24
	v_lshlrev_b32_e32 v80, 1, v10
	v_lshlrev_b32_e32 v82, 1, v12
	v_lshlrev_b32_e32 v92, 1, v22
	s_and_b32 s0, s33, 7
	s_lshr_b32 s1, s33, 6
	s_lshl_b32 s0, s0, 2
	s_add_i32 s0, s0, s1
	s_bfe_u32 s1, s33, 0x30003
	s_lshl_b32 s0, s0, 4
	s_add_i32 s0, s0, s1
	s_cmp_eq_u32 s42, 0x100
	s_cselect_b32 s0, s0, s33
.LBB0_107:
	s_ashr_i32 s10, s0, 7
	s_load_dwordx4 s[16:19], s[78:79], 0x90
	s_ashr_i32 s4, s0, 4
	s_and_b32 s1, s0, 15
	s_ashr_i32 s11, s10, 31
	s_and_b32 s5, s4, 7
	s_lshl_b64 s[40:41], s[10:11], 11
	s_lshl_b32 s10, s1, 7
	s_or_b32 s40, s40, s10
	s_lshl_b32 s10, s5, 2
	v_mov_b32_e32 v4, s10
	s_waitcnt lgkmcnt(0)
	global_load_dword v2, v4, s[16:17]
	s_lshl_b32 s46, s5, 8
	s_mul_i32 s5, s4, 18
	s_add_i32 s5, s1, s5
	s_add_i32 s10, s5, 2
	s_ashr_i32 s11, s10, 31
	s_lshl_b64 s[10:11], s[10:11], 15
	v_lshlrev_b64 v[18:19], 8, v[66:67]
	v_lshl_add_u64 v[22:23], s[40:41], 0, v[70:71]
	v_lshlrev_b64 v[22:23], 11, v[22:23]
	v_lshl_add_u64 v[30:31], s[40:41], 0, v[74:75]
	v_lshlrev_b64 v[26:27], 8, v[70:71]
	v_lshlrev_b64 v[30:31], 11, v[30:31]
	s_lshl_b32 s4, s4, 1
	s_ashr_i32 s5, s4, 31
	s_lshl_b32 s1, s1, 15
	v_mov_b32_e32 v89, v246
	v_mov_b32_e32 v91, v247
	v_mov_b32_e32 v83, v1
	v_mov_b32_e32 v85, v1
	v_mov_b32_e32 v87, v1
	v_mov_b32_e32 v93, v1
	s_waitcnt vmcnt(0)
	v_mul_f32_e32 v3, 0xbfb8aa3b, v2
	v_fma_f32 v5, v2, s12, -v3
	v_rndne_f32_e32 v6, v3
	v_fmac_f32_e32 v5, 0xb2a5705f, v2
	v_sub_f32_e32 v3, v3, v6
	v_add_f32_e32 v3, v3, v5
	v_exp_f32_e32 v3, v3
	v_cvt_i32_f32_e32 v5, v6
	v_cmp_nlt_f32_e32 vcc, s93, v2
	v_ldexp_f32 v3, v3, v5
	s_nop 0
	v_cndmask_b32_e32 v3, 0, v3, vcc
	v_cmp_ngt_f32_e32 vcc, s13, v2
	s_nop 1
	v_cndmask_b32_e32 v5, v222, v3, vcc
	v_add_f32_e32 v6, 1.0, v5
	v_add_f32_e32 v2, -1.0, v6
	v_sub_f32_e32 v3, v2, v6
	v_add_f32_e32 v3, 1.0, v3
	v_sub_f32_e32 v2, v5, v2
	v_add_f32_e32 v7, v2, v3
	v_frexp_mant_f32_e32 v2, v6
	v_cmp_gt_f32_e32 vcc, s15, v2
	v_cvt_f64_f32_e32 v[2:3], v6
	v_frexp_exp_i32_f64_e32 v2, v[2:3]
	v_subbrev_co_u32_e32 v2, vcc, 0, v2, vcc
	v_sub_u32_e32 v3, 0, v2
	v_ldexp_f32 v6, v6, v3
	v_ldexp_f32 v3, v7, v3
	v_add_f32_e32 v7, -1.0, v6
	v_add_f32_e32 v8, 1.0, v7
	v_sub_f32_e32 v8, v6, v8
	v_add_f32_e32 v8, v3, v8
	v_add_f32_e32 v9, v7, v8
	v_sub_f32_e32 v7, v7, v9
	v_add_f32_e32 v7, v8, v7
	v_add_f32_e32 v8, 1.0, v6
	v_add_f32_e32 v10, -1.0, v8
	v_sub_f32_e32 v6, v6, v10
	v_add_f32_e32 v3, v3, v6
	v_add_f32_e32 v6, v8, v3
	v_sub_f32_e32 v8, v8, v6
	v_add_f32_e32 v3, v3, v8
	v_rcp_f32_e32 v8, v6
	v_cvt_f32_i32_e32 v2, v2
	v_cmp_neq_f32_e32 vcc, s14, v5
	v_mul_f32_e32 v10, v9, v8
	v_mul_f32_e32 v11, v6, v10
	v_fma_f32 v12, v10, v6, -v11
	v_fmac_f32_e32 v12, v10, v3
	v_add_f32_e32 v13, v11, v12
	v_sub_f32_e32 v14, v9, v13
	v_sub_f32_e32 v9, v9, v14
	v_sub_f32_e32 v11, v13, v11
	v_sub_f32_e32 v9, v9, v13
	v_add_f32_e32 v7, v7, v9
	v_sub_f32_e32 v9, v11, v12
	v_add_f32_e32 v7, v9, v7
	v_add_f32_e32 v9, v14, v7
	v_mul_f32_e32 v11, v8, v9
	v_mul_f32_e32 v12, v6, v11
	v_fma_f32 v6, v11, v6, -v12
	v_fmac_f32_e32 v6, v11, v3
	v_sub_f32_e32 v3, v14, v9
	v_add_f32_e32 v3, v7, v3
	v_add_f32_e32 v7, v12, v6
	v_sub_f32_e32 v13, v9, v7
	v_sub_f32_e32 v9, v9, v13
	v_sub_f32_e32 v12, v7, v12
	v_sub_f32_e32 v7, v9, v7
	v_add_f32_e32 v3, v3, v7
	v_sub_f32_e32 v6, v12, v6
	v_add_f32_e32 v3, v6, v3
	v_add_f32_e32 v6, v10, v11
	v_add_f32_e32 v3, v13, v3
	v_sub_f32_e32 v7, v6, v10
	v_mul_f32_e32 v3, v8, v3
	v_sub_f32_e32 v7, v11, v7
	v_add_f32_e32 v3, v7, v3
	v_mul_f32_e32 v10, 0x3f317218, v2
	v_add_f32_e32 v7, v6, v3
	v_fma_f32 v11, v2, s51, -v10
	v_mul_f32_e32 v8, v7, v7
	v_fmac_f32_e32 v11, 0xb102e308, v2
	v_sub_f32_e32 v2, v7, v6
	v_fmamk_f32 v9, v8, 0x3e9b6dac, v246
	v_sub_f32_e32 v2, v3, v2
	v_add_f32_e32 v3, v10, v11
	v_fmaak_f32 v9, v8, v9, 0x3f2aaada
	v_sub_f32_e32 v6, v3, v10
	v_ldexp_f32 v10, v7, 1
	v_mul_f32_e32 v7, v7, v8
	v_mul_f32_e32 v7, v7, v9
	v_add_f32_e32 v8, v10, v7
	v_sub_f32_e32 v9, v8, v10
	v_ldexp_f32 v2, v2, 1
	v_sub_f32_e32 v7, v7, v9
	v_add_f32_e32 v2, v2, v7
	v_add_f32_e32 v7, v8, v2
	v_sub_f32_e32 v8, v7, v8
	v_sub_f32_e32 v2, v2, v8
	v_add_f32_e32 v8, v3, v7
	v_sub_f32_e32 v9, v8, v3
	v_sub_f32_e32 v10, v8, v9
	v_sub_f32_e32 v6, v11, v6
	v_sub_f32_e32 v3, v3, v10
	v_sub_f32_e32 v7, v7, v9
	v_add_f32_e32 v3, v7, v3
	v_add_f32_e32 v7, v6, v2
	v_sub_f32_e32 v9, v7, v6
	v_sub_f32_e32 v10, v7, v9
	v_sub_f32_e32 v6, v6, v10
	v_sub_f32_e32 v2, v2, v9
	v_add_f32_e32 v3, v7, v3
	v_add_f32_e32 v2, v2, v6
	v_add_f32_e32 v6, v8, v3
	v_sub_f32_e32 v7, v6, v8
	v_sub_f32_e32 v3, v3, v7
	v_add_f32_e32 v2, v2, v3
	v_add_f32_e32 v2, v6, v2
	v_cndmask_b32_e32 v2, v222, v2, vcc
	v_cmp_lt_f32_e64 vcc, |v5|, s86
	v_lshl_add_u64 v[14:15], s[40:41], 0, v[66:67]
	v_lshlrev_b64 v[14:15], 11, v[14:15]
	v_cndmask_b32_e32 v2, v2, v5, vcc
	v_mul_f32_e32 v79, 0xbfb8aa3b, v2
	global_load_dword v2, v4, s[18:19]
	s_waitcnt vmcnt(0)
; #define LAS __attribute__((address_space(3)))
; __device__ __forceinline__ float log2_gamma(float logit) { return -log1pf(expf(-logit)) * 1.4426950408889634f; }
; __device__ __forceinline__ void r2_phase(KP p, LAS unsigned char* lds, int G, int bid, int wv) {
;     ...
;         float lf = log2_gamma(p->in[18][h]), lb = log2_gamma(p->in[19][h]);
;         asm volatile("" : "+v"(lf), "+v"(lb));
;         {
;             u32x4 kq[4], vq[4];
; #pragma unroll
;             for (int q = 0; q < 4; ++q) { const int c = tid + 512 * q, r = c >> 4, c16 = c & 15;
;                 kq[q] = *(const u32x4*)(kn + (row0 + r) * 1024 + h * 128 + c16 * 8);
;                 vq[q] = *(const u32x4*)(vT + ((size_t)(bh * 18 + 2 + n) * 128 + r) * 128 + c16 * 8); }
; #pragma unroll
;             for (int q = 0; q < 4; ++q) { const int c = tid + 512 * q, r = c >> 4, c16 = c & 15;
;                 *(LAS u32x4*)(Ks + r * 272 + c16 * 16) = kq[q]; *(LAS u32x4*)(Vs + r * 272 + c16 * 16) = vq[q]; }
;         }
;         bf16x8 qf[4];
; #pragma unroll
;         for (int ks = 0; ks < 4; ++ks) qf[ks] = *(const bf16x8*)(qn + (row0 + 16 * wid + fr) * 1024 + h * 128 + 32 * ks + 8 * fq);
	v_mul_f32_e32 v3, 0xbfb8aa3b, v2
	v_fma_f32 v4, v2, s12, -v3
	v_rndne_f32_e32 v5, v3
	v_fmac_f32_e32 v4, 0xb2a5705f, v2
	v_sub_f32_e32 v3, v3, v5
	v_add_f32_e32 v3, v3, v4
	v_exp_f32_e32 v3, v3
	v_cvt_i32_f32_e32 v4, v5
	v_cmp_nlt_f32_e32 vcc, s93, v2
	v_ldexp_f32 v3, v3, v4
	s_nop 0
	v_cndmask_b32_e32 v3, 0, v3, vcc
	v_cmp_ngt_f32_e32 vcc, s13, v2
	s_nop 1
	v_cndmask_b32_e32 v4, v222, v3, vcc
	v_add_f32_e32 v5, 1.0, v4
	v_add_f32_e32 v2, -1.0, v5
	v_sub_f32_e32 v3, v2, v5
	v_add_f32_e32 v3, 1.0, v3
	v_sub_f32_e32 v2, v4, v2
	v_add_f32_e32 v6, v2, v3
	v_frexp_mant_f32_e32 v2, v5
	v_cmp_gt_f32_e32 vcc, s15, v2
	v_cvt_f64_f32_e32 v[2:3], v5
	v_frexp_exp_i32_f64_e32 v2, v[2:3]
	v_subbrev_co_u32_e32 v2, vcc, 0, v2, vcc
	v_sub_u32_e32 v3, 0, v2
	v_ldexp_f32 v5, v5, v3
	v_ldexp_f32 v3, v6, v3
	v_add_f32_e32 v6, -1.0, v5
	v_add_f32_e32 v7, 1.0, v6
	v_sub_f32_e32 v7, v5, v7
	v_add_f32_e32 v7, v3, v7
	v_add_f32_e32 v8, v6, v7
	v_sub_f32_e32 v6, v6, v8
	v_add_f32_e32 v6, v7, v6
	v_add_f32_e32 v7, 1.0, v5
	v_add_f32_e32 v9, -1.0, v7
	v_sub_f32_e32 v5, v5, v9
	v_add_f32_e32 v3, v3, v5
	v_add_f32_e32 v5, v7, v3
	v_sub_f32_e32 v7, v7, v5
	v_add_f32_e32 v3, v3, v7
	v_rcp_f32_e32 v7, v5
	v_cvt_f32_i32_e32 v2, v2
	v_cmp_neq_f32_e32 vcc, s14, v4
	v_mul_f32_e32 v9, v8, v7
	v_mul_f32_e32 v10, v5, v9
	v_fma_f32 v11, v9, v5, -v10
	v_fmac_f32_e32 v11, v9, v3
	v_add_f32_e32 v12, v10, v11
	v_sub_f32_e32 v13, v8, v12
	v_sub_f32_e32 v8, v8, v13
	v_sub_f32_e32 v10, v12, v10
	v_sub_f32_e32 v8, v8, v12
	v_add_f32_e32 v6, v6, v8
	v_sub_f32_e32 v8, v10, v11
	v_add_f32_e32 v6, v8, v6
	v_add_f32_e32 v8, v13, v6
	v_mul_f32_e32 v10, v7, v8
	v_mul_f32_e32 v11, v5, v10
	v_fma_f32 v5, v10, v5, -v11
	v_fmac_f32_e32 v5, v10, v3
	v_sub_f32_e32 v3, v13, v8
	v_add_f32_e32 v3, v6, v3
	v_add_f32_e32 v6, v11, v5
	v_sub_f32_e32 v12, v8, v6
	v_sub_f32_e32 v8, v8, v12
	v_sub_f32_e32 v11, v6, v11
	v_sub_f32_e32 v6, v8, v6
	v_add_f32_e32 v3, v3, v6
	v_sub_f32_e32 v5, v11, v5
	v_add_f32_e32 v3, v5, v3
	v_add_f32_e32 v5, v9, v10
	v_add_f32_e32 v3, v12, v3
	v_sub_f32_e32 v6, v5, v9
	v_mul_f32_e32 v3, v7, v3
	v_sub_f32_e32 v6, v10, v6
	v_add_f32_e32 v3, v6, v3
	v_mul_f32_e32 v9, 0x3f317218, v2
	v_add_f32_e32 v6, v5, v3
	v_fma_f32 v10, v2, s51, -v9
	v_mul_f32_e32 v7, v6, v6
	v_fmac_f32_e32 v10, 0xb102e308, v2
	v_sub_f32_e32 v2, v6, v5
	v_fmamk_f32 v8, v7, 0x3e9b6dac, v246
	v_sub_f32_e32 v2, v3, v2
	v_add_f32_e32 v3, v9, v10
	v_fmaak_f32 v8, v7, v8, 0x3f2aaada
	v_sub_f32_e32 v5, v3, v9
	v_ldexp_f32 v9, v6, 1
	v_mul_f32_e32 v6, v6, v7
	v_mul_f32_e32 v6, v6, v8
	v_add_f32_e32 v7, v9, v6
	v_sub_f32_e32 v8, v7, v9
	v_ldexp_f32 v2, v2, 1
	v_sub_f32_e32 v6, v6, v8
	v_add_f32_e32 v2, v2, v6
	v_add_f32_e32 v6, v7, v2
	v_sub_f32_e32 v7, v6, v7
	v_sub_f32_e32 v2, v2, v7
	v_add_f32_e32 v7, v3, v6
	v_sub_f32_e32 v8, v7, v3
	v_sub_f32_e32 v9, v7, v8
	v_sub_f32_e32 v5, v10, v5
	v_sub_f32_e32 v3, v3, v9
	v_sub_f32_e32 v6, v6, v8
	v_add_f32_e32 v3, v6, v3
	v_add_f32_e32 v6, v5, v2
	v_sub_f32_e32 v8, v6, v5
	v_sub_f32_e32 v9, v6, v8
	v_sub_f32_e32 v5, v5, v9
	v_sub_f32_e32 v2, v2, v8
	v_add_f32_e32 v3, v6, v3
	v_add_f32_e32 v2, v2, v5
	v_add_f32_e32 v5, v7, v3
	v_sub_f32_e32 v6, v5, v7
	v_sub_f32_e32 v3, v3, v6
	v_add_f32_e32 v2, v2, v3
	v_add_f32_e32 v2, v5, v2
	v_cndmask_b32_e32 v2, v222, v2, vcc
	v_cmp_lt_f32_e64 vcc, |v4|, s86
	v_lshl_add_u64 v[6:7], s[40:41], 0, v[62:63]
	v_lshlrev_b64 v[6:7], 11, v[6:7]
	v_cndmask_b32_e32 v2, v2, v4, vcc
	v_mul_f32_e32 v81, 0xbfb8aa3b, v2
	v_lshl_add_u64 v[2:3], v[64:65], 0, s[46:47]
	v_lshl_add_u64 v[4:5], v[68:69], 0, s[10:11]
	v_lshl_add_u64 v[6:7], v[2:3], 0, v[6:7]
	v_lshlrev_b64 v[10:11], 8, v[62:63]
	global_load_dwordx4 v[6:9], v[6:7], off
	v_lshl_add_u64 v[10:11], v[4:5], 0, v[10:11]
	global_load_dwordx4 v[10:13], v[10:11], off
	v_lshl_add_u64 v[14:15], v[2:3], 0, v[14:15]
	global_load_dwordx4 v[14:17], v[14:15], off
	v_lshl_add_u64 v[18:19], v[4:5], 0, v[18:19]
	global_load_dwordx4 v[18:21], v[18:19], off
	v_lshl_add_u64 v[22:23], v[2:3], 0, v[22:23]
	global_load_dwordx4 v[22:25], v[22:23], off
	v_lshl_add_u64 v[26:27], v[4:5], 0, v[26:27]
	v_lshl_add_u64 v[2:3], v[2:3], 0, v[30:31]
	global_load_dwordx4 v[26:29], v[26:27], off
	v_readlane_b32 s10, v254, 19
	global_load_dwordx4 v[30:33], v[2:3], off
	v_lshlrev_b64 v[2:3], 8, v[74:75]
	v_lshl_add_u64 v[2:3], v[4:5], 0, v[2:3]
	global_load_dwordx4 v[2:5], v[2:3], off
	s_waitcnt vmcnt(7)
	ds_write_b128 v193, v[6:9]
	s_waitcnt vmcnt(6)
	ds_write_b128 v193, v[10:13] offset:34816
	s_waitcnt vmcnt(5)
	ds_write_b128 v194, v[14:17]
	s_waitcnt vmcnt(4)
	ds_write_b128 v194, v[18:21] offset:34816
	s_waitcnt vmcnt(3)
	ds_write_b128 v195, v[22:25]
	s_waitcnt vmcnt(2)
	ds_write_b128 v195, v[26:29] offset:34816
	s_waitcnt vmcnt(1)
	ds_write_b128 v196, v[30:33]
	s_waitcnt vmcnt(0)
	ds_write_b128 v196, v[2:5] offset:34816
	v_lshl_add_u64 v[2:3], v[54:55], 0, s[40:41]
	v_lshlrev_b64 v[2:3], 11, v[2:3]
	v_lshl_add_u64 v[2:3], s[2:3], 0, v[2:3]
	v_lshl_add_u64 v[2:3], v[2:3], 0, s[46:47]
	v_lshl_add_u64 v[2:3], v[2:3], 0, v[0:1]
	global_load_dwordx4 v[14:17], v[2:3], off
	global_load_dwordx4 v[10:13], v[2:3], off offset:64
	global_load_dwordx4 v[6:9], v[2:3], off offset:128
	s_nop 0
	global_load_dwordx4 v[2:5], v[2:3], off offset:192
	s_waitcnt lgkmcnt(0)
	s_barrier
; #define LAS __attribute__((address_space(3)))
; __device__ __forceinline__ bf16_t f2bf(float x) { return (bf16_t)(cvt_pk_bf16(x, 0.f) & 0xffffu); }
; __device__ __forceinline__ void r2_phase(KP p, LAS unsigned char* lds, int G, int bid, int wv) {
;     ...
;         __syncthreads();
;         f32x4 sc[8];
; #pragma unroll
;         for (int i = 0; i < 8; ++i) sc[i] = (f32x4){0.f, 0.f, 0.f, 0.f};
; #pragma unroll
;         for (int ks = 0; ks < 4; ++ks)
; #pragma unroll
;             for (int i = 0; i < 8; ++i) {
;                 const bf16x8 kf = *(const LAS bf16x8*)(Ks + (16 * i + fr) * 272 + (32 * ks + 8 * fq) * 2);
;                 sc[i] = __builtin_amdgcn_mfma_f32_16x16x32_bf16(qf[ks], kf, sc[i], 0, 0, 0);
;             }
; #pragma unroll
;         for (int i = 0; i < 8; ++i)
; #pragma unroll
;             for (int j = 0; j < 4; ++j) {
;                 const int diff = (16 * wid + 4 * fq + j) - (16 * i + fr);
;                 const float df = diff >= 0 ? __builtin_amdgcn_exp2f(lf * (float)diff) : 0.f;
;                 const float db = diff <= 0 ? __builtin_amdgcn_exp2f(lb * (float)(-diff)) : 0.f;
;                 *(LAS bf16_t*)(Pw + (4 * fq + j) * 272 + (16 * i + fr) * 2) = f2bf(sc[i][j] * (df + db));
	ds_read_b128 v[18:21], v197
	ds_read_b128 v[94:97], v197 offset:64
	s_waitcnt vmcnt(3) lgkmcnt(1)
	v_mfma_f32_16x16x32_bf16 v[18:21], v[14:17], v[18:21], 0
	ds_read_b128 v[22:25], v197 offset:4352
	ds_read_b128 v[26:29], v197 offset:8704
	ds_read_b128 v[30:33], v197 offset:13056
	s_waitcnt vmcnt(2) lgkmcnt(3)
	v_mfma_f32_16x16x32_bf16 v[18:21], v[10:13], v[94:97], v[18:21]
	ds_read_b128 v[94:97], v197 offset:4416
	ds_read_b128 v[34:37], v197 offset:17408
	ds_read_b128 v[38:41], v197 offset:21760
	s_waitcnt lgkmcnt(5)
	v_mfma_f32_16x16x32_bf16 v[22:25], v[14:17], v[22:25], 0
	ds_read_b128 v[42:45], v197 offset:26112
	ds_read_b128 v[46:49], v197 offset:30464
	v_readlane_b32 s11, v254, 20
	s_waitcnt lgkmcnt(4)
	v_mfma_f32_16x16x32_bf16 v[22:25], v[10:13], v[94:97], v[22:25]
	ds_read_b128 v[94:97], v197 offset:8768
	s_lshl_b64 vcc, s[4:5], 19
	s_or_b32 s4, s4, 1
	v_mfma_f32_16x16x32_bf16 v[26:29], v[14:17], v[26:29], 0
	s_ashr_i32 s5, s4, 31
	s_lshl_b64 s[4:5], s[4:5], 19
	v_mul_f32_e32 v50, v79, v185
	s_waitcnt lgkmcnt(0)
	v_mfma_f32_16x16x32_bf16 v[26:29], v[10:13], v[94:97], v[26:29]
	ds_read_b128 v[94:97], v197 offset:13120
	v_mfma_f32_16x16x32_bf16 v[30:33], v[14:17], v[30:33], 0
	s_waitcnt lgkmcnt(0)
	v_mfma_f32_16x16x32_bf16 v[30:33], v[10:13], v[94:97], v[30:33]
	ds_read_b128 v[94:97], v197 offset:17472
	v_mfma_f32_16x16x32_bf16 v[34:37], v[14:17], v[34:37], 0
	s_waitcnt lgkmcnt(0)
	v_mfma_f32_16x16x32_bf16 v[34:37], v[10:13], v[94:97], v[34:37]
	ds_read_b128 v[94:97], v197 offset:21824
	v_mfma_f32_16x16x32_bf16 v[38:41], v[14:17], v[38:41], 0
	s_waitcnt lgkmcnt(0)
	v_mfma_f32_16x16x32_bf16 v[38:41], v[10:13], v[94:97], v[38:41]
	ds_read_b128 v[94:97], v197 offset:26176
	v_mfma_f32_16x16x32_bf16 v[42:45], v[14:17], v[42:45], 0
	s_waitcnt lgkmcnt(0)
	v_mfma_f32_16x16x32_bf16 v[42:45], v[10:13], v[94:97], v[42:45]
	ds_read_b128 v[94:97], v197 offset:30528
	v_mfma_f32_16x16x32_bf16 v[46:49], v[14:17], v[46:49], 0
	s_waitcnt lgkmcnt(0)
	v_mfma_f32_16x16x32_bf16 v[46:49], v[10:13], v[94:97], v[46:49]
	ds_read_b128 v[94:97], v197 offset:128
	s_waitcnt vmcnt(1) lgkmcnt(0)
	v_mfma_f32_16x16x32_bf16 v[18:21], v[6:9], v[94:97], v[18:21]
	ds_read_b128 v[94:97], v197 offset:4480
	s_waitcnt lgkmcnt(0)
	v_mfma_f32_16x16x32_bf16 v[22:25], v[6:9], v[94:97], v[22:25]
	ds_read_b128 v[94:97], v197 offset:8832
	s_waitcnt lgkmcnt(0)
	v_mfma_f32_16x16x32_bf16 v[26:29], v[6:9], v[94:97], v[26:29]
	ds_read_b128 v[94:97], v197 offset:13184
	s_waitcnt lgkmcnt(0)
	v_mfma_f32_16x16x32_bf16 v[30:33], v[6:9], v[94:97], v[30:33]
	ds_read_b128 v[94:97], v197 offset:17536
	s_waitcnt lgkmcnt(0)
	v_mfma_f32_16x16x32_bf16 v[94:97], v[6:9], v[94:97], v[34:37]
	s_nop 2
	ds_read_b128 v[34:37], v197 offset:21888
	s_waitcnt lgkmcnt(0)
	v_mfma_f32_16x16x32_bf16 v[208:211], v[6:9], v[34:37], v[38:41]
	ds_read_b128 v[34:37], v197 offset:26240
	s_waitcnt lgkmcnt(0)
	v_mfma_f32_16x16x32_bf16 v[224:227], v[6:9], v[34:37], v[42:45]
	ds_read_b128 v[34:37], v197 offset:30592
	s_waitcnt lgkmcnt(0)
	v_mfma_f32_16x16x32_bf16 v[46:49], v[6:9], v[34:37], v[46:49]
	ds_read_b128 v[34:37], v197 offset:192
	s_waitcnt vmcnt(0) lgkmcnt(0)
	v_mfma_f32_16x16x32_bf16 v[228:231], v[2:5], v[34:37], v[18:21]
	s_nop 2
	ds_read_b128 v[18:21], v197 offset:4544
	s_waitcnt lgkmcnt(0)
	v_mfma_f32_16x16x32_bf16 v[42:45], v[2:5], v[18:21], v[22:25]
	ds_read_b128 v[18:21], v197 offset:8896
	s_waitcnt lgkmcnt(0)
	v_mfma_f32_16x16x32_bf16 v[38:41], v[2:5], v[18:21], v[26:29]
	ds_read_b128 v[18:21], v197 offset:13248
	s_waitcnt lgkmcnt(0)
	v_mfma_f32_16x16x32_bf16 v[34:37], v[2:5], v[18:21], v[30:33]
	ds_read_b128 v[18:21], v197 offset:17600
	s_waitcnt lgkmcnt(0)
	v_mfma_f32_16x16x32_bf16 v[30:33], v[2:5], v[18:21], v[94:97]
	ds_read_b128 v[18:21], v197 offset:21952
	s_waitcnt lgkmcnt(0)
	v_mfma_f32_16x16x32_bf16 v[26:29], v[2:5], v[18:21], v[208:211]
	ds_read_b128 v[18:21], v197 offset:26304
	s_waitcnt lgkmcnt(0)
	v_mfma_f32_16x16x32_bf16 v[22:25], v[2:5], v[18:21], v[224:227]
	ds_read_b128 v[18:21], v197 offset:30656
	s_waitcnt lgkmcnt(0)
	v_mfma_f32_16x16x32_bf16 v[18:21], v[2:5], v[18:21], v[46:49]
	s_nop 2
	v_mul_f32_e32 v46, v79, v252
	v_exp_f32_e32 v46, v46
	v_mul_f32_e32 v47, v81, v219
	v_exp_f32_e32 v47, v47
	v_cndmask_b32_e64 v46, 0, v46, s[10:11]
	v_readlane_b32 s10, v254, 17
	v_readlane_b32 s11, v254, 18
	s_nop 1
	v_cndmask_b32_e64 v47, 0, v47, s[10:11]
	v_add_f32_e32 v46, v46, v47
	v_mul_f32_e32 v46, v46, v228
	v_cvt_pk_bf16_f32 v46, v46, v1
	ds_write_b16 v198, v46
	v_mul_f32_e32 v46, v79, v215
	v_exp_f32_e32 v46, v46
	v_mul_f32_e32 v47, v81, v218
	v_readlane_b32 s10, v254, 15
	v_exp_f32_e32 v47, v47
	v_readlane_b32 s11, v254, 16
	s_nop 1
	v_cndmask_b32_e64 v46, 0, v46, s[10:11]
	v_readlane_b32 s10, v254, 13
	v_readlane_b32 s11, v254, 14
	s_nop 1
	v_cndmask_b32_e64 v47, 0, v47, s[10:11]
	v_add_f32_e32 v46, v46, v47
	v_mul_f32_e32 v46, v46, v229
	v_cvt_pk_bf16_f32 v46, v46, v1
	ds_write_b16 v198, v46 offset:272
	v_mul_f32_e32 v46, v79, v106
	v_exp_f32_e32 v46, v46
	v_mul_f32_e32 v47, v81, v107
	v_readlane_b32 s10, v254, 11
	v_exp_f32_e32 v47, v47
	v_readlane_b32 s11, v254, 12
	s_nop 1
	v_cndmask_b32_e64 v46, 0, v46, s[10:11]
	v_readlane_b32 s10, v254, 9
	v_readlane_b32 s11, v254, 10
	s_nop 1
	v_cndmask_b32_e64 v47, 0, v47, s[10:11]
	v_add_f32_e32 v46, v46, v47
	v_mul_f32_e32 v46, v46, v230
	v_cvt_pk_bf16_f32 v46, v46, v1
	ds_write_b16 v198, v46 offset:544
	v_mul_f32_e32 v46, v79, v108
	v_exp_f32_e32 v46, v46
	v_mul_f32_e32 v47, v81, v109
	v_readlane_b32 s10, v254, 7
	v_exp_f32_e32 v47, v47
	v_readlane_b32 s11, v254, 8
	s_nop 1
	v_cndmask_b32_e64 v46, 0, v46, s[10:11]
	v_readlane_b32 s10, v254, 5
; #define LAS __attribute__((address_space(3)))
; __device__ __forceinline__ bf16_t f2bf(float x) { return (bf16_t)(cvt_pk_bf16(x, 0.f) & 0xffffu); }
; __device__ __forceinline__ void r2_phase(KP p, LAS unsigned char* lds, int G, int bid, int wv) {
;     ...
;         for (int i = 0; i < 8; ++i)
; #pragma unroll
;             for (int j = 0; j < 4; ++j) {
;                 const int diff = (16 * wid + 4 * fq + j) - (16 * i + fr);
;                 const float df = diff >= 0 ? __builtin_amdgcn_exp2f(lf * (float)diff) : 0.f;
;                 const float db = diff <= 0 ? __builtin_amdgcn_exp2f(lb * (float)(-diff)) : 0.f;
;                 *(LAS bf16_t*)(Pw + (4 * fq + j) * 272 + (16 * i + fr) * 2) = f2bf(sc[i][j] * (df + db));
	v_readlane_b32 s11, v254, 6
	s_nop 1
	v_cndmask_b32_e64 v47, 0, v47, s[10:11]
	v_add_f32_e32 v46, v46, v47
	v_mul_f32_e32 v46, v46, v231
	v_cvt_pk_bf16_f32 v46, v46, v1
	ds_write_b16 v198, v46 offset:816
	v_mul_f32_e32 v46, v79, v110
	v_exp_f32_e32 v46, v46
	v_mul_f32_e32 v47, v81, v111
	v_readlane_b32 s10, v254, 3
	v_exp_f32_e32 v47, v47
	v_readlane_b32 s11, v254, 4
	s_nop 1
	v_cndmask_b32_e64 v46, 0, v46, s[10:11]
	v_readlane_b32 s10, v254, 1
	v_readlane_b32 s11, v254, 2
	s_nop 1
	v_cndmask_b32_e64 v47, 0, v47, s[10:11]
	v_add_f32_e32 v46, v46, v47
	v_mul_f32_e32 v42, v46, v42
	v_cvt_pk_bf16_f32 v42, v42, v1
	ds_write_b16 v199, v42
	v_mul_f32_e32 v42, v79, v112
	v_exp_f32_e32 v42, v42
	v_mul_f32_e32 v46, v81, v113
	v_readlane_b32 s10, v254, 21
	v_exp_f32_e32 v46, v46
	v_readlane_b32 s11, v254, 22
	s_nop 1
	v_cndmask_b32_e64 v42, 0, v42, s[10:11]
	v_readlane_b32 s10, v254, 25
	v_readlane_b32 s11, v254, 26
	s_nop 1
	v_cndmask_b32_e64 v46, 0, v46, s[10:11]
	v_add_f32_e32 v42, v42, v46
	v_mul_f32_e32 v42, v42, v43
	v_cvt_pk_bf16_f32 v42, v42, v1
	ds_write_b16 v199, v42 offset:272
	v_mul_f32_e32 v42, v79, v114
	v_exp_f32_e32 v42, v42
	v_mul_f32_e32 v43, v81, v115
	v_readlane_b32 s10, v254, 31
	v_exp_f32_e32 v43, v43
	v_readlane_b32 s11, v254, 32
	s_nop 1
	v_cndmask_b32_e64 v42, 0, v42, s[10:11]
	v_readlane_b32 s10, v254, 29
	v_readlane_b32 s11, v254, 30
	s_nop 1
	v_cndmask_b32_e64 v43, 0, v43, s[10:11]
	v_add_f32_e32 v42, v42, v43
	v_mul_f32_e32 v42, v42, v44
	v_cvt_pk_bf16_f32 v42, v42, v1
	ds_write_b16 v199, v42 offset:544
	v_mul_f32_e32 v42, v79, v116
	v_exp_f32_e32 v42, v42
	v_mul_f32_e32 v43, v81, v117
	v_readlane_b32 s10, v254, 27
	v_exp_f32_e32 v43, v43
	v_readlane_b32 s11, v254, 28
	s_nop 1
	v_cndmask_b32_e64 v42, 0, v42, s[10:11]
	v_readlane_b32 s10, v254, 33
	v_readlane_b32 s11, v254, 34
	s_nop 1
	v_cndmask_b32_e64 v43, 0, v43, s[10:11]
	v_add_f32_e32 v42, v42, v43
	v_mul_f32_e32 v42, v42, v45
	v_cvt_pk_bf16_f32 v42, v42, v1
	ds_write_b16 v199, v42 offset:816
	v_mul_f32_e32 v42, v79, v118
	v_exp_f32_e32 v42, v42
	v_mul_f32_e32 v43, v81, v119
	v_readlane_b32 s10, v254, 23
	v_exp_f32_e32 v43, v43
	v_readlane_b32 s11, v254, 24
	s_nop 1
	v_cndmask_b32_e64 v42, 0, v42, s[10:11]
	v_readlane_b32 s10, v254, 39
	v_readlane_b32 s11, v254, 40
	s_nop 1
	v_cndmask_b32_e64 v43, 0, v43, s[10:11]
	v_add_f32_e32 v42, v42, v43
	v_mul_f32_e32 v38, v42, v38
	v_cvt_pk_bf16_f32 v38, v38, v1
	ds_write_b16 v200, v38
	v_mul_f32_e32 v38, v79, v120
	v_exp_f32_e32 v38, v38
	v_mul_f32_e32 v42, v81, v121
	v_readlane_b32 s10, v254, 41
	v_exp_f32_e32 v42, v42
	v_readlane_b32 s11, v254, 42
	s_nop 1
	v_cndmask_b32_e64 v38, 0, v38, s[10:11]
	v_readlane_b32 s10, v254, 43
	v_readlane_b32 s11, v254, 44
	s_nop 1
	v_cndmask_b32_e64 v42, 0, v42, s[10:11]
	v_add_f32_e32 v38, v38, v42
	v_mul_f32_e32 v38, v38, v39
	v_cvt_pk_bf16_f32 v38, v38, v1
	ds_write_b16 v200, v38 offset:272
	v_mul_f32_e32 v38, v79, v122
	v_exp_f32_e32 v38, v38
	v_mul_f32_e32 v39, v81, v123
	v_readlane_b32 s10, v254, 45
	v_exp_f32_e32 v39, v39
	v_readlane_b32 s11, v254, 46
	s_nop 1
	v_cndmask_b32_e64 v38, 0, v38, s[10:11]
	v_readlane_b32 s10, v254, 47
	v_readlane_b32 s11, v254, 48
	s_nop 1
	v_cndmask_b32_e64 v39, 0, v39, s[10:11]
	v_add_f32_e32 v38, v38, v39
	v_mul_f32_e32 v38, v38, v40
	v_cvt_pk_bf16_f32 v38, v38, v1
	ds_write_b16 v200, v38 offset:544
	v_mul_f32_e32 v38, v79, v124
	v_exp_f32_e32 v38, v38
	v_mul_f32_e32 v39, v81, v125
	v_readlane_b32 s10, v254, 49
	v_exp_f32_e32 v39, v39
	v_readlane_b32 s11, v254, 50
	s_nop 1
	v_cndmask_b32_e64 v38, 0, v38, s[10:11]
	v_readlane_b32 s10, v254, 51
	v_readlane_b32 s11, v254, 52
	s_nop 1
	v_cndmask_b32_e64 v39, 0, v39, s[10:11]
	v_add_f32_e32 v38, v38, v39
	v_mul_f32_e32 v38, v38, v41
	v_cvt_pk_bf16_f32 v38, v38, v1
	ds_write_b16 v200, v38 offset:816
	v_mul_f32_e32 v38, v79, v126
	v_exp_f32_e32 v38, v38
	v_mul_f32_e32 v39, v81, v127
	v_readlane_b32 s10, v254, 53
	v_exp_f32_e32 v39, v39
	v_readlane_b32 s11, v254, 54
	s_nop 1
	v_cndmask_b32_e64 v38, 0, v38, s[10:11]
	v_readlane_b32 s10, v254, 55
	v_readlane_b32 s11, v254, 56
	s_nop 1
	v_cndmask_b32_e64 v39, 0, v39, s[10:11]
	v_add_f32_e32 v38, v38, v39
	v_mul_f32_e32 v34, v38, v34
	v_cvt_pk_bf16_f32 v34, v34, v1
	ds_write_b16 v201, v34
	v_mul_f32_e32 v34, v79, v128
	v_exp_f32_e32 v34, v34
	v_mul_f32_e32 v38, v81, v129
	v_readlane_b32 s10, v254, 57
	v_exp_f32_e32 v38, v38
	v_readlane_b32 s11, v254, 58
	s_nop 1
	v_cndmask_b32_e64 v34, 0, v34, s[10:11]
	v_readlane_b32 s10, v254, 59
	v_readlane_b32 s11, v254, 60
	s_nop 1
	v_cndmask_b32_e64 v38, 0, v38, s[10:11]
	v_add_f32_e32 v34, v34, v38
	v_mul_f32_e32 v34, v34, v35
	v_cvt_pk_bf16_f32 v34, v34, v1
	ds_write_b16 v201, v34 offset:272
	v_mul_f32_e32 v34, v79, v130
	v_exp_f32_e32 v34, v34
	v_mul_f32_e32 v35, v81, v131
	v_readlane_b32 s10, v254, 61
	v_exp_f32_e32 v35, v35
	v_readlane_b32 s11, v254, 62
	s_nop 1
	v_cndmask_b32_e64 v34, 0, v34, s[10:11]
	v_readlane_b32 s10, v254, 63
	v_readlane_b32 s11, v255, 0
	s_nop 1
	v_cndmask_b32_e64 v35, 0, v35, s[10:11]
	v_add_f32_e32 v34, v34, v35
	v_mul_f32_e32 v34, v34, v36
	v_cvt_pk_bf16_f32 v34, v34, v1
	ds_write_b16 v201, v34 offset:544
	v_mul_f32_e32 v34, v79, v132
	v_exp_f32_e32 v34, v34
	v_mul_f32_e32 v35, v81, v133
	v_readlane_b32 s10, v255, 1
	v_exp_f32_e32 v35, v35
	v_readlane_b32 s11, v255, 2
	s_nop 1
	v_cndmask_b32_e64 v34, 0, v34, s[10:11]
	v_readlane_b32 s10, v255, 3
	v_readlane_b32 s11, v255, 4
	s_nop 1
	v_cndmask_b32_e64 v35, 0, v35, s[10:11]
	v_add_f32_e32 v34, v34, v35
	v_mul_f32_e32 v34, v34, v37
	v_cvt_pk_bf16_f32 v34, v34, v1
	ds_write_b16 v201, v34 offset:816
	v_mul_f32_e32 v34, v79, v134
; #define LAS __attribute__((address_space(3)))
; __device__ __forceinline__ bf16_t f2bf(float x) { return (bf16_t)(cvt_pk_bf16(x, 0.f) & 0xffffu); }
; __device__ __forceinline__ void r2_phase(KP p, LAS unsigned char* lds, int G, int bid, int wv) {
;     ...
;     for (int u = bid; u < 512; u += G) {
;     ...
;         for (int i = 0; i < 8; ++i)
; #pragma unroll
;             for (int j = 0; j < 4; ++j) {
;                 const int diff = (16 * wid + 4 * fq + j) - (16 * i + fr);
;                 const float df = diff >= 0 ? __builtin_amdgcn_exp2f(lf * (float)diff) : 0.f;
;                 const float db = diff <= 0 ? __builtin_amdgcn_exp2f(lb * (float)(-diff)) : 0.f;
;                 *(LAS bf16_t*)(Pw + (4 * fq + j) * 272 + (16 * i + fr) * 2) = f2bf(sc[i][j] * (df + db));
	v_exp_f32_e32 v34, v34
	v_mul_f32_e32 v35, v81, v135
	v_readlane_b32 s10, v255, 5
	v_exp_f32_e32 v35, v35
	v_readlane_b32 s11, v255, 6
	s_nop 1
	v_cndmask_b32_e64 v34, 0, v34, s[10:11]
	v_readlane_b32 s10, v255, 7
	v_readlane_b32 s11, v255, 8
	s_nop 1
	v_cndmask_b32_e64 v35, 0, v35, s[10:11]
	v_add_f32_e32 v34, v34, v35
	v_mul_f32_e32 v30, v34, v30
	v_cvt_pk_bf16_f32 v30, v30, v1
	ds_write_b16 v202, v30
	v_mul_f32_e32 v30, v79, v136
	v_exp_f32_e32 v30, v30
	v_mul_f32_e32 v34, v81, v137
	v_readlane_b32 s10, v255, 9
	v_exp_f32_e32 v34, v34
	v_readlane_b32 s11, v255, 10
	s_nop 1
	v_cndmask_b32_e64 v30, 0, v30, s[10:11]
	v_readlane_b32 s10, v255, 11
	v_readlane_b32 s11, v255, 12
	s_nop 1
	v_cndmask_b32_e64 v34, 0, v34, s[10:11]
	v_add_f32_e32 v30, v30, v34
	v_mul_f32_e32 v30, v30, v31
	v_cvt_pk_bf16_f32 v30, v30, v1
	ds_write_b16 v202, v30 offset:272
	v_mul_f32_e32 v30, v79, v138
	v_exp_f32_e32 v30, v30
	v_mul_f32_e32 v31, v81, v139
	v_readlane_b32 s10, v255, 13
	v_exp_f32_e32 v31, v31
	v_readlane_b32 s11, v255, 14
	s_nop 1
	v_cndmask_b32_e64 v30, 0, v30, s[10:11]
	v_readlane_b32 s10, v255, 15
	v_readlane_b32 s11, v255, 16
	s_nop 1
	v_cndmask_b32_e64 v31, 0, v31, s[10:11]
	v_add_f32_e32 v30, v30, v31
	v_mul_f32_e32 v30, v30, v32
	v_cvt_pk_bf16_f32 v30, v30, v1
	ds_write_b16 v202, v30 offset:544
	v_mul_f32_e32 v30, v79, v140
	v_exp_f32_e32 v30, v30
	v_mul_f32_e32 v31, v81, v141
	v_readlane_b32 s10, v255, 17
	v_exp_f32_e32 v31, v31
	v_readlane_b32 s11, v255, 18
	s_nop 1
	v_cndmask_b32_e64 v30, 0, v30, s[10:11]
	v_readlane_b32 s10, v255, 19
	v_readlane_b32 s11, v255, 20
	s_nop 1
	v_cndmask_b32_e64 v31, 0, v31, s[10:11]
	v_add_f32_e32 v30, v30, v31
	v_mul_f32_e32 v30, v30, v33
	v_cvt_pk_bf16_f32 v30, v30, v1
	ds_write_b16 v202, v30 offset:816
	v_mul_f32_e32 v30, v79, v142
	v_exp_f32_e32 v30, v30
	v_mul_f32_e32 v31, v81, v143
	v_readlane_b32 s10, v255, 21
	v_exp_f32_e32 v31, v31
	v_readlane_b32 s11, v255, 22
	s_nop 1
	v_cndmask_b32_e64 v30, 0, v30, s[10:11]
	v_readlane_b32 s10, v255, 23
	v_readlane_b32 s11, v255, 24
	s_nop 1
	v_cndmask_b32_e64 v31, 0, v31, s[10:11]
	v_add_f32_e32 v30, v30, v31
	v_mul_f32_e32 v26, v30, v26
	v_cvt_pk_bf16_f32 v26, v26, v1
	ds_write_b16 v203, v26
	v_mul_f32_e32 v26, v79, v144
	v_exp_f32_e32 v26, v26
	v_mul_f32_e32 v30, v81, v145
	v_readlane_b32 s10, v255, 25
	v_exp_f32_e32 v30, v30
	v_readlane_b32 s11, v255, 26
	s_nop 1
	v_cndmask_b32_e64 v26, 0, v26, s[10:11]
	v_readlane_b32 s10, v255, 27
	v_readlane_b32 s11, v255, 28
	s_nop 1
	v_cndmask_b32_e64 v30, 0, v30, s[10:11]
	v_add_f32_e32 v26, v26, v30
	v_mul_f32_e32 v26, v26, v27
	v_cvt_pk_bf16_f32 v26, v26, v1
	ds_write_b16 v203, v26 offset:272
	v_mul_f32_e32 v26, v79, v146
	v_exp_f32_e32 v26, v26
	v_mul_f32_e32 v27, v81, v147
	v_readlane_b32 s10, v255, 29
	v_exp_f32_e32 v27, v27
	v_readlane_b32 s11, v255, 30
	s_nop 1
	v_cndmask_b32_e64 v26, 0, v26, s[10:11]
	v_readlane_b32 s10, v255, 31
	v_readlane_b32 s11, v255, 32
	s_nop 1
	v_cndmask_b32_e64 v27, 0, v27, s[10:11]
	v_add_f32_e32 v26, v26, v27
	v_mul_f32_e32 v26, v26, v28
	v_cvt_pk_bf16_f32 v26, v26, v1
	ds_write_b16 v203, v26 offset:544
	v_mul_f32_e32 v26, v79, v148
	v_exp_f32_e32 v26, v26
	v_mul_f32_e32 v27, v81, v149
	v_readlane_b32 s10, v255, 33
	v_exp_f32_e32 v27, v27
	v_readlane_b32 s11, v255, 34
	s_nop 1
	v_cndmask_b32_e64 v26, 0, v26, s[10:11]
	v_readlane_b32 s10, v255, 35
	v_readlane_b32 s11, v255, 36
	s_nop 1
	v_cndmask_b32_e64 v27, 0, v27, s[10:11]
	v_add_f32_e32 v26, v26, v27
	v_mul_f32_e32 v26, v26, v29
	v_cvt_pk_bf16_f32 v26, v26, v1
	ds_write_b16 v203, v26 offset:816
	v_mul_f32_e32 v26, v79, v150
	v_exp_f32_e32 v26, v26
	v_mul_f32_e32 v27, v81, v151
	v_readlane_b32 s10, v255, 37
	v_exp_f32_e32 v27, v27
	v_readlane_b32 s11, v255, 38
	s_nop 1
	v_cndmask_b32_e64 v26, 0, v26, s[10:11]
	v_readlane_b32 s10, v255, 39
	v_readlane_b32 s11, v255, 40
	s_nop 1
	v_cndmask_b32_e64 v27, 0, v27, s[10:11]
	v_add_f32_e32 v26, v26, v27
	v_mul_f32_e32 v22, v26, v22
	v_cvt_pk_bf16_f32 v22, v22, v1
	ds_write_b16 v204, v22
	v_mul_f32_e32 v22, v79, v152
	v_exp_f32_e32 v22, v22
	v_mul_f32_e32 v26, v81, v153
	v_readlane_b32 s10, v255, 41
	v_exp_f32_e32 v26, v26
	v_readlane_b32 s11, v255, 42
	s_nop 1
	v_cndmask_b32_e64 v22, 0, v22, s[10:11]
	v_readlane_b32 s10, v255, 43
	v_readlane_b32 s11, v255, 44
	s_nop 1
	v_cndmask_b32_e64 v26, 0, v26, s[10:11]
	v_add_f32_e32 v22, v22, v26
	v_mul_f32_e32 v22, v22, v23
	v_cvt_pk_bf16_f32 v22, v22, v1
	ds_write_b16 v204, v22 offset:272
	v_mul_f32_e32 v22, v79, v154
	v_mul_f32_e32 v23, v81, v155
	v_exp_f32_e32 v22, v22
	v_exp_f32_e32 v23, v23
	s_add_u32 s10, s8, s4
	s_addc_u32 s11, s9, s5
	v_cndmask_b32_e64 v22, 0, v22, s[6:7]
	v_cndmask_b32_e64 v23, 0, v23, s[54:55]
	v_add_f32_e32 v22, v22, v23
	v_mul_f32_e32 v22, v22, v24
	v_cvt_pk_bf16_f32 v22, v22, v1
	ds_write_b16 v204, v22 offset:544
	v_mul_f32_e32 v22, v79, v156
	v_mul_f32_e32 v23, v81, v157
	v_exp_f32_e32 v22, v22
	v_exp_f32_e32 v23, v23
	s_add_u32 s4, s8, vcc_lo
	s_addc_u32 s5, s9, vcc_hi
	v_cndmask_b32_e64 v22, 0, v22, s[64:65]
	v_cndmask_b32_e64 v23, 0, v23, s[20:21]
	v_add_f32_e32 v22, v22, v23
	v_mul_f32_e32 v22, v22, v25
	v_cvt_pk_bf16_f32 v22, v22, v1
	ds_write_b16 v204, v22 offset:816
	v_mul_f32_e32 v22, v79, v158
	v_mul_f32_e32 v23, v81, v159
	v_exp_f32_e32 v22, v22
	v_exp_f32_e32 v23, v23
	s_add_u32 s4, s4, s1
	s_addc_u32 s5, s5, 0
	v_cndmask_b32_e64 v22, 0, v22, s[22:23]
	v_cndmask_b32_e64 v23, 0, v23, s[24:25]
	v_add_f32_e32 v22, v22, v23
	v_mul_f32_e32 v18, v22, v18
	v_cvt_pk_bf16_f32 v18, v18, v1
	ds_write_b16 v205, v18
	v_mul_f32_e32 v18, v79, v160
	v_mul_f32_e32 v22, v81, v161
	v_exp_f32_e32 v18, v18
	v_exp_f32_e32 v22, v22
	s_add_u32 s10, s10, s1
	s_addc_u32 s11, s11, 0
	v_cndmask_b32_e64 v18, 0, v18, s[26:27]
	v_cndmask_b32_e64 v22, 0, v22, s[28:29]
	v_add_f32_e32 v18, v18, v22
	v_mul_f32_e32 v18, v18, v19
	v_cvt_pk_bf16_f32 v18, v18, v1
	ds_write_b16 v205, v18 offset:272
	v_mul_f32_e32 v18, v79, v163
	v_mul_f32_e32 v19, v81, v178
	v_exp_f32_e32 v18, v18
	v_exp_f32_e32 v19, v19
	s_cmp_eq_u32 s42, 0x100
	s_cbranch_scc0 .Lr2_generic
	s_add_i32 s0, s0, 8
	s_bitcmp0_b32 s0, 3
	s_branch .Lr2_latch_done
; #define LAS __attribute__((address_space(3)))
; __device__ __forceinline__ void r2_phase(KP p, LAS unsigned char* lds, int G, int bid, int wv) {
;     ...
;         __syncthreads();
;         bf16x8 pf[4];
; #pragma unroll
;         for (int ks = 0; ks < 4; ++ks) pf[ks] = *(const LAS bf16x8*)(Pw + fr * 272 + (32 * ks + 8 * fq) * 2);
;         f32x4 o[8];
; #pragma unroll
;         for (int i = 0; i < 8; ++i) o[i] = (f32x4){0.f, 0.f, 0.f, 0.f};
; #pragma unroll
;         for (int ks = 0; ks < 4; ++ks)
; #pragma unroll
;             for (int i = 0; i < 8; ++i) {
;                 const bf16x8 vf = *(const LAS bf16x8*)(Vs + (16 * i + fr) * 272 + (32 * ks + 8 * fq) * 2);
;                 o[i] = __builtin_amdgcn_mfma_f32_16x16x32_bf16(pf[ks], vf, o[i], 0, 0, 0);
;             }
;         const bf16_t* Sf = ST + ((size_t)(bh * 2 + 0) * 16 + n) * 16384; const bf16_t* Sb = ST + ((size_t)(bh * 2 + 1) * 16 + n) * 16384;
;         float sfac[4], sbac[4];
; #pragma unroll
;         for (int j = 0; j < 4; ++j) { const int c = 16 * wid + 4 * fq + j; sfac[j] = __builtin_amdgcn_exp2f(lf * (float)(c + 1)); sbac[j] = __builtin_amdgcn_exp2f(lb * (float)(128 - c)); }
.Lr2_generic:
	s_add_i32 s0, s0, s42
	s_cmpk_gt_i32 s0, 0x1ff
.Lr2_latch_done:
	v_cndmask_b32_e64 v18, 0, v18, s[30:31]
	v_cndmask_b32_e64 v19, 0, v19, s[34:35]
	v_add_f32_e32 v18, v18, v19
	v_mul_f32_e32 v18, v18, v20
	v_cvt_pk_bf16_f32 v18, v18, v1
	ds_write_b16 v205, v18 offset:544
	v_mul_f32_e32 v18, v79, v182
	v_mul_f32_e32 v19, v81, v184
	v_exp_f32_e32 v18, v18
	v_exp_f32_e32 v19, v19
	v_cndmask_b32_e64 v18, 0, v18, s[36:37]
	v_cndmask_b32_e64 v19, 0, v19, s[38:39]
	v_add_f32_e32 v18, v18, v19
	v_mul_f32_e32 v18, v18, v21
	v_cvt_pk_bf16_f32 v18, v18, v1
	ds_write_b16 v205, v18 offset:816
	s_waitcnt lgkmcnt(0)
	s_barrier
	ds_read_b128 v[18:21], v206
	ds_read_b128 v[22:25], v206 offset:64
	ds_read_b128 v[26:29], v206 offset:128
	ds_read_b128 v[94:97], v206 offset:192
	ds_read_b128 v[30:33], v197 offset:34816
	ds_read_b128 v[34:37], v197 offset:39168
	ds_read_b128 v[38:41], v197 offset:43520
	ds_read_b128 v[42:45], v197 offset:47872
	ds_read_b128 v[46:49], v197 offset:52224
	ds_read_b128 v[208:211], v197 offset:56576
	ds_read_b128 v[224:227], v197 offset:60928
	ds_read_b128 v[228:231], v197 offset:65280
	s_waitcnt lgkmcnt(7)
	v_mfma_f32_16x16x32_bf16 v[30:33], v[18:21], v[30:33], 0
	s_waitcnt lgkmcnt(6)
	v_mfma_f32_16x16x32_bf16 v[34:37], v[18:21], v[34:37], 0
	s_waitcnt lgkmcnt(5)
	v_mfma_f32_16x16x32_bf16 v[38:41], v[18:21], v[38:41], 0
	s_waitcnt lgkmcnt(4)
	v_mfma_f32_16x16x32_bf16 v[42:45], v[18:21], v[42:45], 0
	s_waitcnt lgkmcnt(3)
	v_mfma_f32_16x16x32_bf16 v[46:49], v[18:21], v[46:49], 0
	s_waitcnt lgkmcnt(2)
	v_mfma_f32_16x16x32_bf16 v[208:211], v[18:21], v[208:211], 0
	s_waitcnt lgkmcnt(1)
	v_mfma_f32_16x16x32_bf16 v[224:227], v[18:21], v[224:227], 0
	s_waitcnt lgkmcnt(0)
	v_mfma_f32_16x16x32_bf16 v[18:21], v[18:21], v[228:231], 0
	ds_read_b128 v[228:231], v197 offset:34880
	s_waitcnt lgkmcnt(0)
	v_mfma_f32_16x16x32_bf16 v[30:33], v[22:25], v[228:231], v[30:33]
	ds_read_b128 v[228:231], v197 offset:39232
	s_waitcnt lgkmcnt(0)
	v_mfma_f32_16x16x32_bf16 v[34:37], v[22:25], v[228:231], v[34:37]
	ds_read_b128 v[228:231], v197 offset:43584
	s_waitcnt lgkmcnt(0)
	v_mfma_f32_16x16x32_bf16 v[38:41], v[22:25], v[228:231], v[38:41]
	ds_read_b128 v[228:231], v197 offset:47936
	s_waitcnt lgkmcnt(0)
	v_mfma_f32_16x16x32_bf16 v[42:45], v[22:25], v[228:231], v[42:45]
	ds_read_b128 v[228:231], v197 offset:52288
	s_waitcnt lgkmcnt(0)
	v_mfma_f32_16x16x32_bf16 v[46:49], v[22:25], v[228:231], v[46:49]
	ds_read_b128 v[228:231], v197 offset:56640
	s_waitcnt lgkmcnt(0)
	v_mfma_f32_16x16x32_bf16 v[208:211], v[22:25], v[228:231], v[208:211]
	ds_read_b128 v[228:231], v197 offset:60992
	s_waitcnt lgkmcnt(0)
	v_mfma_f32_16x16x32_bf16 v[224:227], v[22:25], v[228:231], v[224:227]
	ds_read_b128 v[228:231], v197 offset:65344
	s_waitcnt lgkmcnt(0)
	v_mfma_f32_16x16x32_bf16 v[18:21], v[22:25], v[228:231], v[18:21]
	ds_read_b128 v[22:25], v197 offset:34944
	s_waitcnt lgkmcnt(0)
	v_mfma_f32_16x16x32_bf16 v[22:25], v[26:29], v[22:25], v[30:33]
	s_nop 2
	ds_read_b128 v[30:33], v197 offset:39296
	s_waitcnt lgkmcnt(0)
	v_mfma_f32_16x16x32_bf16 v[30:33], v[26:29], v[30:33], v[34:37]
	s_nop 2
	ds_read_b128 v[34:37], v197 offset:43648
	s_waitcnt lgkmcnt(0)
	v_mfma_f32_16x16x32_bf16 v[34:37], v[26:29], v[34:37], v[38:41]
	s_nop 2
	ds_read_b128 v[38:41], v197 offset:48000
	s_waitcnt lgkmcnt(0)
	v_mfma_f32_16x16x32_bf16 v[228:231], v[26:29], v[38:41], v[42:45]
	ds_read_b128 v[38:41], v197 offset:52352
	s_waitcnt lgkmcnt(0)
	v_mfma_f32_16x16x32_bf16 v[232:235], v[26:29], v[38:41], v[46:49]
	ds_read_b128 v[38:41], v197 offset:56704
	s_waitcnt lgkmcnt(0)
	v_mfma_f32_16x16x32_bf16 v[208:211], v[26:29], v[38:41], v[208:211]
	ds_read_b128 v[38:41], v197 offset:61056
	s_waitcnt lgkmcnt(0)
	v_mfma_f32_16x16x32_bf16 v[224:227], v[26:29], v[38:41], v[224:227]
	ds_read_b128 v[38:41], v197 offset:65408
	s_waitcnt lgkmcnt(0)
	v_mfma_f32_16x16x32_bf16 v[18:21], v[26:29], v[38:41], v[18:21]
	ds_read_b128 v[26:29], v197 offset:35008
	s_waitcnt lgkmcnt(0)
	v_mfma_f32_16x16x32_bf16 v[46:49], v[94:97], v[26:29], v[22:25]
	s_nop 2
	ds_read_b128 v[22:25], v197 offset:39360
	s_waitcnt lgkmcnt(0)
	v_mfma_f32_16x16x32_bf16 v[42:45], v[94:97], v[22:25], v[30:33]
	ds_read_b128 v[22:25], v197 offset:43712
	s_waitcnt lgkmcnt(0)
	v_mfma_f32_16x16x32_bf16 v[38:41], v[94:97], v[22:25], v[34:37]
	ds_read_b128 v[22:25], v197 offset:48064
	s_waitcnt lgkmcnt(0)
	v_mfma_f32_16x16x32_bf16 v[34:37], v[94:97], v[22:25], v[228:231]
	ds_read_b128 v[22:25], v197 offset:52416
	s_waitcnt lgkmcnt(0)
	v_mfma_f32_16x16x32_bf16 v[30:33], v[94:97], v[22:25], v[232:235]
	ds_read_b128 v[22:25], v197 offset:56768
	s_waitcnt lgkmcnt(0)
	v_mfma_f32_16x16x32_bf16 v[26:29], v[94:97], v[22:25], v[208:211]
	ds_read_b128 v[22:25], v197 offset:61120
	s_nop 1
	ds_read_b128 v[208:211], v197 offset:65472
	s_waitcnt lgkmcnt(1)
	v_mfma_f32_16x16x32_bf16 v[22:25], v[94:97], v[22:25], v[224:227]
	s_nop 2
	v_exp_f32_e32 v225, v50
	v_mul_f32_e32 v50, v81, v186
	v_exp_f32_e32 v226, v50
	v_mul_f32_e32 v50, v79, v187
	v_exp_f32_e32 v213, v50
	v_mul_f32_e32 v50, v81, v188
	v_exp_f32_e32 v224, v50
	v_mul_f32_e32 v50, v79, v189
	s_waitcnt lgkmcnt(0)
	v_mfma_f32_16x16x32_bf16 v[18:21], v[94:97], v[208:211], v[18:21]
	v_exp_f32_e32 v211, v50
	v_mul_f32_e32 v50, v81, v190
	v_exp_f32_e32 v212, v50
	v_mul_f32_e32 v50, v79, v191
	v_exp_f32_e32 v209, v50
	v_mul_f32_e32 v50, v81, v192
	v_lshl_add_u64 v[96:97], s[4:5], 0, v[0:1]
	v_mov_b32_e32 v79, v1
	v_exp_f32_e32 v210, v50
	v_lshl_add_u64 v[94:95], s[10:11], 0, v[0:1]
	v_lshl_add_u64 v[50:51], v[96:97], 0, v[78:79]
	v_lshl_add_u64 v[58:59], v[94:95], 0, v[78:79]
	global_load_dwordx4 v[228:231], v[50:51], off
	global_load_dwordx4 v[232:235], v[58:59], off
	global_load_dwordx4 v[236:239], v[50:51], off offset:64
	global_load_dwordx4 v[240:243], v[58:59], off offset:64
	global_load_dwordx4 v[244:247], v[50:51], off offset:128
	global_load_dwordx4 v[248:251], v[58:59], off offset:128
	s_nop 0
	global_load_dwordx4 v[50:53], v[50:51], off offset:192
	s_nop 0
	global_load_dwordx4 v[58:61], v[58:59], off offset:192
	s_waitcnt vmcnt(6)
; #define R2_SLOAD(dst, i) do { _Pragma("unroll") for (int ks = 0; ks < 4; ++ks) { dst[0][ks] = *(const bf16x8*)(Sf + (16 * (i) + fr) * 128 + 32 * ks + 8 * fq); \
;                                                                              dst[1][ks] = *(const bf16x8*)(Sb + (16 * (i) + fr) * 128 + 32 * ks + 8 * fq); } } while (0)
; __device__ __forceinline__ void r2_phase(KP p, LAS unsigned char* lds, int G, int bid, int wv) {
;     ...
;         const bf16_t* Sf = ST + ((size_t)(bh * 2 + 0) * 16 + n) * 16384; const bf16_t* Sb = ST + ((size_t)(bh * 2 + 1) * 16 + n) * 16384;
;         float sfac[4], sbac[4];
; #pragma unroll
;         for (int j = 0; j < 4; ++j) { const int c = 16 * wid + 4 * fq + j; sfac[j] = __builtin_amdgcn_exp2f(lf * (float)(c + 1)); sbac[j] = __builtin_amdgcn_exp2f(lb * (float)(128 - c)); }
;     ...
; #pragma unroll
;         for (int i = 0; i < 8; ++i) {
;             bf16x8 sA[2][4];
;             R2_SLOAD(sA, i);
;             R2_SUSE(sA, i);
;         }
	v_mfma_f32_16x16x32_bf16 v[232:235], v[14:17], v[232:235], 0
	v_mov_b32_e32 v81, v1
	v_lshl_add_u64 v[102:103], v[94:95], 0, v[80:81]
	v_mfma_f32_16x16x32_bf16 v[228:231], v[14:17], v[228:231], 0
	s_waitcnt vmcnt(4)
	v_mfma_f32_16x16x32_bf16 v[232:235], v[10:13], v[240:243], v[232:235]
	v_mfma_f32_16x16x32_bf16 v[228:231], v[10:13], v[236:239], v[228:231]
	s_waitcnt vmcnt(2)
	v_mfma_f32_16x16x32_bf16 v[232:235], v[6:9], v[248:251], v[232:235]
	v_mfma_f32_16x16x32_bf16 v[228:231], v[6:9], v[244:247], v[228:231]
	s_waitcnt vmcnt(0)
	v_mfma_f32_16x16x32_bf16 v[58:61], v[2:5], v[58:61], v[232:235]
	v_mfma_f32_16x16x32_bf16 v[50:53], v[2:5], v[50:53], v[228:231]
	s_nop 6
	v_mul_f32_e32 v58, v226, v58
	v_fmac_f32_e32 v58, v225, v50
	v_add_f32_e32 v227, v46, v58
	v_mul_f32_e32 v46, v224, v59
	v_fmac_f32_e32 v46, v213, v51
	v_add_f32_e32 v79, v47, v46
	v_mul_f32_e32 v46, v212, v60
	v_fmac_f32_e32 v46, v211, v52
	v_add_f32_e32 v47, v48, v46
	v_mul_f32_e32 v46, v210, v61
	v_fmac_f32_e32 v46, v209, v53
	v_lshl_add_u64 v[52:53], v[96:97], 0, v[80:81]
	v_add_f32_e32 v46, v49, v46
	global_load_dwordx4 v[48:51], v[52:53], off
	global_load_dwordx4 v[58:61], v[102:103], off
	global_load_dwordx4 v[228:231], v[52:53], off offset:64
	global_load_dwordx4 v[232:235], v[102:103], off offset:64
	global_load_dwordx4 v[236:239], v[52:53], off offset:128
	global_load_dwordx4 v[240:243], v[102:103], off offset:128
	global_load_dwordx4 v[244:247], v[52:53], off offset:192
	global_load_dwordx4 v[248:251], v[102:103], off offset:192
	s_waitcnt vmcnt(6)
	v_mfma_f32_16x16x32_bf16 v[58:61], v[14:17], v[58:61], 0
	v_lshl_add_u64 v[102:103], v[94:95], 0, v[82:83]
	v_mfma_f32_16x16x32_bf16 v[48:51], v[14:17], v[48:51], 0
	s_waitcnt vmcnt(4)
	v_mfma_f32_16x16x32_bf16 v[58:61], v[10:13], v[232:235], v[58:61]
	v_mfma_f32_16x16x32_bf16 v[48:51], v[10:13], v[228:231], v[48:51]
	s_waitcnt vmcnt(2)
	v_mfma_f32_16x16x32_bf16 v[58:61], v[6:9], v[240:243], v[58:61]
	v_mfma_f32_16x16x32_bf16 v[48:51], v[6:9], v[236:239], v[48:51]
	s_waitcnt vmcnt(0)
	v_mfma_f32_16x16x32_bf16 v[58:61], v[2:5], v[248:251], v[58:61]
	v_mfma_f32_16x16x32_bf16 v[48:51], v[2:5], v[244:247], v[48:51]
	s_nop 6
	v_mul_f32_e32 v52, v226, v58
	v_fmac_f32_e32 v52, v225, v48
	v_add_f32_e32 v228, v42, v52
	v_mul_f32_e32 v42, v224, v59
	v_fmac_f32_e32 v42, v213, v49
	v_add_f32_e32 v207, v43, v42
	v_mul_f32_e32 v42, v212, v60
	v_fmac_f32_e32 v42, v211, v50
	v_add_f32_e32 v44, v44, v42
	v_mul_f32_e32 v42, v210, v61
	v_lshl_add_u64 v[52:53], v[96:97], 0, v[82:83]
	v_fmac_f32_e32 v42, v209, v51
	global_load_dwordx4 v[48:51], v[52:53], off
	global_load_dwordx4 v[58:61], v[102:103], off
	global_load_dwordx4 v[230:233], v[52:53], off offset:64
	global_load_dwordx4 v[234:237], v[102:103], off offset:64
	global_load_dwordx4 v[238:241], v[52:53], off offset:128
	global_load_dwordx4 v[242:245], v[102:103], off offset:128
	global_load_dwordx4 v[246:249], v[52:53], off offset:192
	s_nop 0
	global_load_dwordx4 v[102:105], v[102:103], off offset:192
	s_waitcnt vmcnt(6)
	v_mfma_f32_16x16x32_bf16 v[58:61], v[14:17], v[58:61], 0
	v_add_f32_e32 v42, v45, v42
	v_lshl_add_u64 v[52:53], v[94:95], 0, v[84:85]
	v_mfma_f32_16x16x32_bf16 v[48:51], v[14:17], v[48:51], 0
	s_waitcnt vmcnt(4)
	v_mfma_f32_16x16x32_bf16 v[58:61], v[10:13], v[234:237], v[58:61]
	v_mfma_f32_16x16x32_bf16 v[48:51], v[10:13], v[230:233], v[48:51]
	s_waitcnt vmcnt(2)
	v_mfma_f32_16x16x32_bf16 v[58:61], v[6:9], v[242:245], v[58:61]
	v_mfma_f32_16x16x32_bf16 v[48:51], v[6:9], v[238:241], v[48:51]
	s_waitcnt vmcnt(0)
	v_mfma_f32_16x16x32_bf16 v[58:61], v[2:5], v[102:105], v[58:61]
	v_mfma_f32_16x16x32_bf16 v[48:51], v[2:5], v[246:249], v[48:51]
	s_nop 6
	v_mul_f32_e32 v43, v226, v58
	v_fmac_f32_e32 v43, v225, v48
	v_add_f32_e32 v229, v38, v43
	v_mul_f32_e32 v38, v224, v59
	v_fmac_f32_e32 v38, v213, v49
	v_add_f32_e32 v208, v39, v38
	v_mul_f32_e32 v38, v212, v60
	v_fmac_f32_e32 v38, v211, v50
	v_add_f32_e32 v45, v40, v38
	v_mul_f32_e32 v38, v210, v61
	v_fmac_f32_e32 v38, v209, v51
	v_add_f32_e32 v38, v41, v38
	v_lshl_add_u64 v[40:41], v[96:97], 0, v[84:85]
	global_load_dwordx4 v[48:51], v[40:41], off
	global_load_dwordx4 v[58:61], v[52:53], off
	global_load_dwordx4 v[102:105], v[40:41], off offset:64
	global_load_dwordx4 v[230:233], v[52:53], off offset:64
	global_load_dwordx4 v[234:237], v[40:41], off offset:128
	global_load_dwordx4 v[238:241], v[52:53], off offset:128
	global_load_dwordx4 v[242:245], v[40:41], off offset:192
	global_load_dwordx4 v[246:249], v[52:53], off offset:192
	s_waitcnt vmcnt(6)
	v_mfma_f32_16x16x32_bf16 v[58:61], v[14:17], v[58:61], 0
	v_lshl_add_u64 v[40:41], v[96:97], 0, v[86:87]
	v_mfma_f32_16x16x32_bf16 v[48:51], v[14:17], v[48:51], 0
	s_waitcnt vmcnt(4)
	v_mfma_f32_16x16x32_bf16 v[58:61], v[10:13], v[230:233], v[58:61]
	v_mfma_f32_16x16x32_bf16 v[48:51], v[10:13], v[102:105], v[48:51]
	s_waitcnt vmcnt(2)
	v_mfma_f32_16x16x32_bf16 v[58:61], v[6:9], v[238:241], v[58:61]
	v_mfma_f32_16x16x32_bf16 v[48:51], v[6:9], v[234:237], v[48:51]
	s_waitcnt vmcnt(0)
	v_mfma_f32_16x16x32_bf16 v[58:61], v[2:5], v[246:249], v[58:61]
	v_mfma_f32_16x16x32_bf16 v[48:51], v[2:5], v[242:245], v[48:51]
	v_lshl_add_u64 v[244:245], v[94:95], 0, v[86:87]
	s_nop 5
	v_mul_f32_e32 v39, v226, v58
	v_fmac_f32_e32 v39, v225, v48
	v_add_f32_e32 v230, v34, v39
	v_mul_f32_e32 v34, v224, v59
	v_fmac_f32_e32 v34, v213, v49
	v_add_f32_e32 v85, v35, v34
	v_mul_f32_e32 v34, v212, v60
	v_fmac_f32_e32 v34, v211, v50
	v_add_f32_e32 v48, v36, v34
	v_mul_f32_e32 v34, v210, v61
	v_fmac_f32_e32 v34, v209, v51
	v_add_f32_e32 v39, v37, v34
	global_load_dwordx4 v[34:37], v[40:41], off
	global_load_dwordx4 v[50:53], v[244:245], off
	global_load_dwordx4 v[58:61], v[40:41], off offset:64
	global_load_dwordx4 v[102:105], v[244:245], off offset:64
	global_load_dwordx4 v[232:235], v[40:41], off offset:128
	global_load_dwordx4 v[236:239], v[244:245], off offset:128
	global_load_dwordx4 v[240:243], v[40:41], off offset:192
	s_nop 0
	global_load_dwordx4 v[244:247], v[244:245], off offset:192
	s_waitcnt vmcnt(6)
; #define R2_SLOAD(dst, i) do { _Pragma("unroll") for (int ks = 0; ks < 4; ++ks) { dst[0][ks] = *(const bf16x8*)(Sf + (16 * (i) + fr) * 128 + 32 * ks + 8 * fq); \
;                                                                              dst[1][ks] = *(const bf16x8*)(Sb + (16 * (i) + fr) * 128 + 32 * ks + 8 * fq); } } while (0)
; __device__ __forceinline__ void r2_phase(KP p, LAS unsigned char* lds, int G, int bid, int wv) {
;     ...
; #pragma unroll
;         for (int i = 0; i < 8; ++i) {
;             bf16x8 sA[2][4];
;             R2_SLOAD(sA, i);
;             R2_SUSE(sA, i);
;         }
	v_mfma_f32_16x16x32_bf16 v[50:53], v[14:17], v[50:53], 0
	v_mfma_f32_16x16x32_bf16 v[34:37], v[14:17], v[34:37], 0
	s_waitcnt vmcnt(4)
	v_mfma_f32_16x16x32_bf16 v[50:53], v[10:13], v[102:105], v[50:53]
	v_mfma_f32_16x16x32_bf16 v[34:37], v[10:13], v[58:61], v[34:37]
	s_waitcnt vmcnt(2)
	v_mfma_f32_16x16x32_bf16 v[50:53], v[6:9], v[236:239], v[50:53]
	v_mfma_f32_16x16x32_bf16 v[34:37], v[6:9], v[232:235], v[34:37]
	s_waitcnt vmcnt(0)
	v_mfma_f32_16x16x32_bf16 v[50:53], v[2:5], v[244:247], v[50:53]
	v_mov_b32_e32 v246, v89
	v_mov_b32_e32 v89, v1
	v_lshl_add_u64 v[236:237], v[96:97], 0, v[88:89]
	v_mfma_f32_16x16x32_bf16 v[34:37], v[2:5], v[240:243], v[34:37]
	v_lshl_add_u64 v[240:241], v[94:95], 0, v[88:89]
	s_nop 2
	v_mul_f32_e32 v40, v226, v50
	v_mov_b32_e32 v247, v91
	v_mov_b32_e32 v91, v1
	s_nop 0
	v_fmac_f32_e32 v40, v225, v34
	v_add_f32_e32 v231, v30, v40
	v_mul_f32_e32 v30, v224, v51
	v_fmac_f32_e32 v30, v213, v35
	v_add_f32_e32 v87, v31, v30
	v_mul_f32_e32 v30, v212, v52
	v_fmac_f32_e32 v30, v211, v36
	v_add_f32_e32 v49, v32, v30
	v_mul_f32_e32 v30, v210, v53
	v_fmac_f32_e32 v30, v209, v37
	v_add_f32_e32 v40, v33, v30
	global_load_dwordx4 v[30:33], v[236:237], off
	global_load_dwordx4 v[34:37], v[240:241], off
	global_load_dwordx4 v[50:53], v[236:237], off offset:64
	global_load_dwordx4 v[58:61], v[240:241], off offset:64
	global_load_dwordx4 v[102:105], v[236:237], off offset:128
	global_load_dwordx4 v[232:235], v[240:241], off offset:128
	s_nop 0
	global_load_dwordx4 v[236:239], v[236:237], off offset:192
	s_nop 0
	global_load_dwordx4 v[240:243], v[240:241], off offset:192
	s_waitcnt vmcnt(6)
	v_mfma_f32_16x16x32_bf16 v[34:37], v[14:17], v[34:37], 0
	v_mfma_f32_16x16x32_bf16 v[30:33], v[14:17], v[30:33], 0
	s_waitcnt vmcnt(4)
	v_mfma_f32_16x16x32_bf16 v[34:37], v[10:13], v[58:61], v[34:37]
	v_mfma_f32_16x16x32_bf16 v[30:33], v[10:13], v[50:53], v[30:33]
	s_waitcnt vmcnt(2)
	v_mfma_f32_16x16x32_bf16 v[34:37], v[6:9], v[232:235], v[34:37]
	v_lshl_add_u64 v[234:235], v[96:97], 0, v[90:91]
	v_mfma_f32_16x16x32_bf16 v[30:33], v[6:9], v[102:105], v[30:33]
	s_waitcnt vmcnt(0)
	v_mfma_f32_16x16x32_bf16 v[34:37], v[2:5], v[240:243], v[34:37]
	v_mfma_f32_16x16x32_bf16 v[30:33], v[2:5], v[236:239], v[30:33]
	v_lshl_add_u64 v[238:239], v[94:95], 0, v[90:91]
	s_nop 5
	v_mul_f32_e32 v34, v226, v34
	v_fmac_f32_e32 v34, v225, v30
	v_add_f32_e32 v232, v26, v34
	v_mul_f32_e32 v26, v224, v35
	v_fmac_f32_e32 v26, v213, v31
	v_add_f32_e32 v89, v27, v26
	v_mul_f32_e32 v26, v212, v36
	v_fmac_f32_e32 v26, v211, v32
	v_add_f32_e32 v81, v28, v26
	v_mul_f32_e32 v26, v210, v37
	v_fmac_f32_e32 v26, v209, v33
	v_add_f32_e32 v41, v29, v26
	global_load_dwordx4 v[26:29], v[234:235], off
	global_load_dwordx4 v[30:33], v[238:239], off
	global_load_dwordx4 v[34:37], v[234:235], off offset:64
	global_load_dwordx4 v[50:53], v[238:239], off offset:64
	global_load_dwordx4 v[58:61], v[234:235], off offset:128
	global_load_dwordx4 v[102:105], v[238:239], off offset:128
	s_nop 0
	global_load_dwordx4 v[234:237], v[234:235], off offset:192
	s_nop 0
	global_load_dwordx4 v[238:241], v[238:239], off offset:192
	s_waitcnt vmcnt(6)
	v_mfma_f32_16x16x32_bf16 v[30:33], v[14:17], v[30:33], 0
	v_mfma_f32_16x16x32_bf16 v[26:29], v[14:17], v[26:29], 0
	s_waitcnt vmcnt(4)
	v_mfma_f32_16x16x32_bf16 v[30:33], v[10:13], v[50:53], v[30:33]
	v_mfma_f32_16x16x32_bf16 v[26:29], v[10:13], v[34:37], v[26:29]
	s_waitcnt vmcnt(2)
	v_mfma_f32_16x16x32_bf16 v[30:33], v[6:9], v[102:105], v[30:33]
	v_mfma_f32_16x16x32_bf16 v[26:29], v[6:9], v[58:61], v[26:29]
	s_waitcnt vmcnt(0)
	v_mfma_f32_16x16x32_bf16 v[30:33], v[2:5], v[238:241], v[30:33]
	v_mfma_f32_16x16x32_bf16 v[26:29], v[2:5], v[234:237], v[26:29]
	s_nop 6
	v_mul_f32_e32 v30, v226, v30
	v_fmac_f32_e32 v30, v225, v26
	v_add_f32_e32 v233, v22, v30
	v_mul_f32_e32 v22, v224, v31
	v_fmac_f32_e32 v22, v213, v27
	v_add_f32_e32 v91, v23, v22
	v_mul_f32_e32 v22, v212, v32
	v_fmac_f32_e32 v22, v211, v28
	v_add_f32_e32 v83, v24, v22
	v_mul_f32_e32 v22, v210, v33
	v_fmac_f32_e32 v22, v209, v29
	v_add_f32_e32 v43, v25, v22
	v_lshl_add_u64 v[22:23], v[96:97], 0, v[92:93]
	v_lshl_add_u64 v[24:25], v[94:95], 0, v[92:93]
	global_load_dwordx4 v[50:53], v[22:23], off
	global_load_dwordx4 v[58:61], v[24:25], off
	global_load_dwordx4 v[94:97], v[22:23], off offset:64
	global_load_dwordx4 v[102:105], v[24:25], off offset:64
	global_load_dwordx4 v[34:37], v[22:23], off offset:128
	global_load_dwordx4 v[30:33], v[24:25], off offset:128
	global_load_dwordx4 v[26:29], v[22:23], off offset:192
	s_nop 0
	global_load_dwordx4 v[22:25], v[24:25], off offset:192
	s_waitcnt vmcnt(7)
	v_mfma_f32_16x16x32_bf16 v[50:53], v[14:17], v[50:53], 0
	s_waitcnt vmcnt(6)
	v_mfma_f32_16x16x32_bf16 v[14:17], v[14:17], v[58:61], 0
	s_waitcnt vmcnt(5)
	v_mfma_f32_16x16x32_bf16 v[50:53], v[10:13], v[94:97], v[50:53]
	s_waitcnt vmcnt(4)
	v_mfma_f32_16x16x32_bf16 v[10:13], v[10:13], v[102:105], v[14:17]
	s_waitcnt vmcnt(3)
	v_mfma_f32_16x16x32_bf16 v[14:17], v[6:9], v[34:37], v[50:53]
	s_waitcnt vmcnt(2)
	v_mfma_f32_16x16x32_bf16 v[6:9], v[6:9], v[30:33], v[10:13]
	s_waitcnt vmcnt(1)
	v_mfma_f32_16x16x32_bf16 v[10:13], v[2:5], v[26:29], v[14:17]
	s_waitcnt vmcnt(0)
; __device__ __forceinline__ bf16_t f2bf(float x) { return (bf16_t)(cvt_pk_bf16(x, 0.f) & 0xffffu); }
; __device__ __forceinline__ float bf2f(unsigned b) { return __uint_as_float(b << 16); }
; __device__ __forceinline__ float silu_fast(float x) { return x * __builtin_amdgcn_rcpf(1.0f + __expf(-x)); }
; #define R2_SLOAD(dst, i) do { _Pragma("unroll") for (int ks = 0; ks < 4; ++ks) { dst[0][ks] = *(const bf16x8*)(Sf + (16 * (i) + fr) * 128 + 32 * ks + 8 * fq); \
;                                                                              dst[1][ks] = *(const bf16x8*)(Sb + (16 * (i) + fr) * 128 + 32 * ks + 8 * fq); } } while (0)
; __device__ __forceinline__ void r2_phase(KP p, LAS unsigned char* lds, int G, int bid, int wv) {
;     ...
; #pragma unroll
;         for (int i = 0; i < 8; ++i) {
;             bf16x8 sA[2][4];
;             R2_SLOAD(sA, i);
;             R2_SUSE(sA, i);
;         }
;     ...
;         unsigned short gq[4][8];
; #pragma unroll
;         for (int j = 0; j < 4; ++j)
; #pragma unroll
;             for (int i = 0; i < 8; ++i) gq[j][i] = pr[(row0 + 16 * wid + 4 * fq + j) * 4096 + h * 128 + 16 * i + fr];
; #pragma unroll
;         for (int j = 0; j < 4; ++j) {
;             float s = 0.f;
; #pragma unroll
;             for (int i = 0; i < 8; ++i) s += o[i][j];
;             s += __shfl_xor(s, 1); s += __shfl_xor(s, 2); s += __shfl_xor(s, 4); s += __shfl_xor(s, 8);
;             const float mu = s * (1.0f / 128.0f);
;             float q = 0.f;
; #pragma unroll
;             for (int i = 0; i < 8; ++i) { const float d = o[i][j] - mu; q += d * d; }
;             q += __shfl_xor(q, 1); q += __shfl_xor(q, 2); q += __shfl_xor(q, 4); q += __shfl_xor(q, 8);
;             const float rs = 1.0f / sqrtf(q * (1.0f / 128.0f) + 1e-5f);
;             const size_t row = row0 + 16 * wid + 4 * fq + j;
; #pragma unroll
;             for (int i = 0; i < 8; ++i) {
;                 const float gg = bf2f((unsigned)gq[j][i]);
;                 Y[row * DM + h * 128 + 16 * i + fr] = f2bf((o[i][j] - mu) * rs * silu_fast(gg));
	v_mfma_f32_16x16x32_bf16 v[2:5], v[2:5], v[22:25], v[6:9]
	s_nop 7
	v_mul_f32_e32 v2, v226, v2
	v_fmac_f32_e32 v2, v225, v10
	v_add_f32_e32 v52, v18, v2
	v_mul_f32_e32 v2, v224, v3
	v_fmac_f32_e32 v2, v213, v11
	v_add_f32_e32 v29, v19, v2
	v_mul_f32_e32 v2, v212, v4
	v_fmac_f32_e32 v2, v211, v12
	v_add_f32_e32 v22, v20, v2
	v_mul_f32_e32 v2, v210, v5
	v_fmac_f32_e32 v2, v209, v13
	v_add_f32_e32 v20, v21, v2
	v_add_f32_e32 v21, 0, v227
	v_add_f32_e32 v21, v21, v228
	v_add_f32_e32 v21, v21, v229
	v_add_f32_e32 v21, v21, v230
	v_add_f32_e32 v21, v21, v231
	v_lshl_add_u64 v[18:19], s[40:41], 0, v[56:57]
	v_add_f32_e32 v21, v21, v232
	v_lshl_add_u64 v[2:3], v[72:73], 0, s[46:47]
	v_lshlrev_b64 v[4:5], 13, v[18:19]
	v_or_b32_e32 v8, 1, v18
	v_mov_b32_e32 v9, v19
	v_add_f32_e32 v21, v21, v233
	v_lshl_add_u64 v[16:17], v[2:3], 0, v[4:5]
	v_lshlrev_b64 v[4:5], 13, v[8:9]
	v_or_b32_e32 v6, 2, v18
	v_mov_b32_e32 v7, v19
	v_add_f32_e32 v21, v21, v52
	v_lshl_add_u64 v[14:15], v[2:3], 0, v[4:5]
	v_lshlrev_b64 v[4:5], 13, v[6:7]
	ds_bpermute_b32 v23, v98, v21
	v_lshl_add_u64 v[12:13], v[2:3], 0, v[4:5]
	v_or_b32_e32 v4, 3, v18
	v_mov_b32_e32 v5, v19
	v_lshlrev_b64 v[10:11], 13, v[4:5]
	v_lshl_add_u64 v[10:11], v[2:3], 0, v[10:11]
	v_lshl_add_u64 v[2:3], v[76:77], 0, s[46:47]
	v_lshlrev_b64 v[18:19], 12, v[18:19]
	v_lshl_add_u64 v[50:51], v[2:3], 0, v[18:19]
	global_load_ushort v18, v[16:17], off
	s_waitcnt lgkmcnt(0)
	v_add_f32_e32 v21, v21, v23
	ds_bpermute_b32 v23, v99, v21
	v_lshlrev_b64 v[8:9], 12, v[8:9]
	v_lshl_add_u64 v[8:9], v[2:3], 0, v[8:9]
	v_lshlrev_b64 v[6:7], 12, v[6:7]
	v_lshl_add_u64 v[6:7], v[2:3], 0, v[6:7]
	s_waitcnt lgkmcnt(0)
	v_add_f32_e32 v21, v21, v23
	ds_bpermute_b32 v23, v100, v21
	v_lshlrev_b64 v[4:5], 12, v[4:5]
	v_lshl_add_u64 v[2:3], v[2:3], 0, v[4:5]
	s_waitcnt lgkmcnt(0)
	v_add_f32_e32 v21, v21, v23
	ds_bpermute_b32 v23, v101, v21
	s_waitcnt lgkmcnt(0)
	v_add_f32_e32 v21, v21, v23
	v_fmac_f32_e32 v228, 0xbc000000, v21
	v_fmac_f32_e32 v227, 0xbc000000, v21
	v_mul_f32_e32 v23, v228, v228
	v_fmac_f32_e32 v23, v227, v227
	v_fmac_f32_e32 v229, 0xbc000000, v21
	v_fmac_f32_e32 v23, v229, v229
	v_fmac_f32_e32 v230, 0xbc000000, v21
	v_fmac_f32_e32 v23, v230, v230
	v_fmac_f32_e32 v231, 0xbc000000, v21
	v_fmac_f32_e32 v23, v231, v231
	v_fmac_f32_e32 v232, 0xbc000000, v21
	v_fmac_f32_e32 v23, v232, v232
	v_fmac_f32_e32 v233, 0xbc000000, v21
	v_fmac_f32_e32 v23, v233, v233
	v_fmac_f32_e32 v52, 0xbc000000, v21
	v_fmac_f32_e32 v23, v52, v52
	ds_bpermute_b32 v21, v98, v23
	s_waitcnt lgkmcnt(0)
	v_add_f32_e32 v21, v23, v21
	ds_bpermute_b32 v23, v99, v21
	s_waitcnt lgkmcnt(0)
	v_add_f32_e32 v21, v21, v23
	ds_bpermute_b32 v23, v100, v21
	s_waitcnt lgkmcnt(0)
	v_add_f32_e32 v21, v21, v23
	ds_bpermute_b32 v23, v101, v21
	s_waitcnt lgkmcnt(0)
	v_add_f32_e32 v21, v21, v23
	v_fmamk_f32 v21, v21, 0x3c000000, v247
	v_cmp_gt_f32_e64 s[40:41], s77, v21
	v_mul_f32_e32 v23, 0x4f800000, v21
	s_waitcnt vmcnt(0)
	v_lshlrev_b32_e32 v18, 16, v18
	v_cndmask_b32_e64 v21, v21, v23, s[40:41]
	v_sqrt_f32_e32 v23, v21
	s_nop 0
	v_add_u32_e32 v24, -1, v23
	v_fma_f32 v25, -v24, v23, v21
	v_cmp_ge_f32_e32 vcc, 0, v25
	v_add_u32_e32 v25, 1, v23
	s_nop 0
	v_cndmask_b32_e32 v24, v23, v24, vcc
	v_fma_f32 v23, -v25, v23, v21
	v_cmp_lt_f32_e32 vcc, 0, v23
	s_nop 1
	v_cndmask_b32_e32 v23, v24, v25, vcc
	v_mul_f32_e32 v24, 0x37800000, v23
	v_cndmask_b32_e64 v23, v23, v24, s[40:41]
	v_cmp_class_f32_e32 vcc, v21, v216
	s_nop 1
	v_cndmask_b32_e32 v21, v23, v21, vcc
	v_div_scale_f32 v23, s[4:5], v21, v21, 1.0
	v_rcp_f32_e32 v24, v23
	s_nop 0
	v_fma_f32 v25, -v23, v24, 1.0
	v_fmac_f32_e32 v24, v25, v24
	v_div_scale_f32 v25, vcc, 1.0, v21, 1.0
	v_mul_f32_e32 v26, v25, v24
	v_fma_f32 v27, -v23, v26, v25
	v_fmac_f32_e32 v26, v27, v24
	v_fma_f32 v23, -v23, v26, v25
	v_div_fmas_f32 v23, v23, v24, v26
	v_div_fixup_f32 v53, v23, v21, 1.0
	v_mul_f32_e32 v21, 0xbfb8aa3b, v18
	v_exp_f32_e32 v21, v21
	v_mul_f32_e32 v19, v227, v53
	v_mul_f32_e32 v52, v52, v53
	v_add_f32_e32 v21, 1.0, v21
	v_rcp_f32_e32 v21, v21
	s_nop 0
	v_mul_f32_e32 v18, v21, v18
	v_mul_f32_e32 v18, v18, v19
	v_cvt_pk_bf16_f32 v58, v18, v1
	global_load_ushort v59, v[16:17], off offset:32
	global_load_ushort v60, v[16:17], off offset:64
	global_load_ushort v61, v[16:17], off offset:96
	global_load_ushort v93, v[16:17], off offset:128
	global_load_ushort v94, v[16:17], off offset:160
	global_load_ushort v95, v[16:17], off offset:192
	global_load_ushort v96, v[16:17], off offset:224
	global_load_ushort v37, v[14:15], off
	global_load_ushort v36, v[14:15], off offset:32
	global_load_ushort v35, v[14:15], off offset:64
	global_load_ushort v34, v[14:15], off offset:96
	global_load_ushort v33, v[14:15], off offset:128
	global_load_ushort v32, v[14:15], off offset:160
	global_load_ushort v31, v[14:15], off offset:192
	global_load_ushort v30, v[14:15], off offset:224
	global_load_ushort v28, v[12:13], off
	global_load_ushort v27, v[12:13], off offset:32
	global_load_ushort v26, v[12:13], off offset:64
	global_load_ushort v25, v[12:13], off offset:96
	global_load_ushort v24, v[12:13], off offset:128
	global_load_ushort v23, v[12:13], off offset:160
	global_load_ushort v21, v[12:13], off offset:192
	global_load_ushort v19, v[12:13], off offset:224
	global_load_ushort v18, v[10:11], off
	global_load_ushort v17, v[10:11], off offset:32
	global_load_ushort v16, v[10:11], off offset:64
	global_load_ushort v15, v[10:11], off offset:96
	global_load_ushort v14, v[10:11], off offset:128
	global_load_ushort v13, v[10:11], off offset:160
	global_load_ushort v12, v[10:11], off offset:192
	s_nop 0
	global_load_ushort v10, v[10:11], off offset:224
	s_waitcnt vmcnt(30)
; __device__ __forceinline__ bf16_t f2bf(float x) { return (bf16_t)(cvt_pk_bf16(x, 0.f) & 0xffffu); }
; __device__ __forceinline__ float bf2f(unsigned b) { return __uint_as_float(b << 16); }
; __device__ __forceinline__ float silu_fast(float x) { return x * __builtin_amdgcn_rcpf(1.0f + __expf(-x)); }
; __device__ __forceinline__ void r2_phase(KP p, LAS unsigned char* lds, int G, int bid, int wv) {
;     ...
;         unsigned short gq[4][8];
; #pragma unroll
;         for (int j = 0; j < 4; ++j)
; #pragma unroll
;             for (int i = 0; i < 8; ++i) gq[j][i] = pr[(row0 + 16 * wid + 4 * fq + j) * 4096 + h * 128 + 16 * i + fr];
; #pragma unroll
;         for (int j = 0; j < 4; ++j) {
;             float s = 0.f;
; #pragma unroll
;             for (int i = 0; i < 8; ++i) s += o[i][j];
;             s += __shfl_xor(s, 1); s += __shfl_xor(s, 2); s += __shfl_xor(s, 4); s += __shfl_xor(s, 8);
;             const float mu = s * (1.0f / 128.0f);
;             float q = 0.f;
; #pragma unroll
;             for (int i = 0; i < 8; ++i) { const float d = o[i][j] - mu; q += d * d; }
;             q += __shfl_xor(q, 1); q += __shfl_xor(q, 2); q += __shfl_xor(q, 4); q += __shfl_xor(q, 8);
;             const float rs = 1.0f / sqrtf(q * (1.0f / 128.0f) + 1e-5f);
;             const size_t row = row0 + 16 * wid + 4 * fq + j;
; #pragma unroll
;             for (int i = 0; i < 8; ++i) {
;                 const float gg = bf2f((unsigned)gq[j][i]);
;                 Y[row * DM + h * 128 + 16 * i + fr] = f2bf((o[i][j] - mu) * rs * silu_fast(gg));
;             }
	v_lshlrev_b32_e32 v11, 16, v59
	v_mul_f32_e32 v59, 0xbfb8aa3b, v11
	v_exp_f32_e32 v59, v59
	global_store_short v[50:51], v58, off
	v_mul_f32_e32 v58, v228, v53
	v_add_f32_e32 v59, 1.0, v59
	v_rcp_f32_e32 v59, v59
	s_waitcnt vmcnt(24)
	v_lshlrev_b32_e32 v37, 16, v37
	s_waitcnt vmcnt(23)
	v_lshlrev_b32_e32 v36, 16, v36
	s_waitcnt vmcnt(22)
	v_lshlrev_b32_e32 v35, 16, v35
	v_mul_f32_e32 v11, v59, v11
	v_mul_f32_e32 v11, v11, v58
	v_cvt_pk_bf16_f32 v11, v11, v1
	global_store_short v[50:51], v11, off offset:32
	v_lshlrev_b32_e32 v11, 16, v60
	v_mul_f32_e32 v59, 0xbfb8aa3b, v11
	v_exp_f32_e32 v59, v59
	v_mul_f32_e32 v58, v229, v53
	s_waitcnt vmcnt(22)
	v_lshlrev_b32_e32 v34, 16, v34
	s_waitcnt vmcnt(21)
	v_lshlrev_b32_e32 v33, 16, v33
	v_add_f32_e32 v59, 1.0, v59
	v_rcp_f32_e32 v59, v59
	s_waitcnt vmcnt(20)
	v_lshlrev_b32_e32 v32, 16, v32
	s_waitcnt vmcnt(19)
	v_lshlrev_b32_e32 v31, 16, v31
	s_waitcnt vmcnt(18)
	v_lshlrev_b32_e32 v30, 16, v30
	v_mul_f32_e32 v11, v59, v11
	v_mul_f32_e32 v11, v11, v58
	v_cvt_pk_bf16_f32 v11, v11, v1
	global_store_short v[50:51], v11, off offset:64
	v_lshlrev_b32_e32 v11, 16, v61
	v_mul_f32_e32 v59, 0xbfb8aa3b, v11
	v_exp_f32_e32 v59, v59
	v_mul_f32_e32 v58, v230, v53
	s_waitcnt vmcnt(10)
	v_lshlrev_b32_e32 v4, 16, v18
	v_add_f32_e32 v59, 1.0, v59
	v_rcp_f32_e32 v59, v59
	s_nop 0
	v_mul_f32_e32 v11, v59, v11
	v_mul_f32_e32 v11, v11, v58
	v_cvt_pk_bf16_f32 v11, v11, v1
	global_store_short v[50:51], v11, off offset:96
	v_lshlrev_b32_e32 v11, 16, v93
	v_mul_f32_e32 v59, 0xbfb8aa3b, v11
	v_exp_f32_e32 v59, v59
	v_mul_f32_e32 v58, v231, v53
	v_add_f32_e32 v59, 1.0, v59
	v_rcp_f32_e32 v59, v59
	s_nop 0
	v_mul_f32_e32 v11, v59, v11
	v_mul_f32_e32 v11, v11, v58
	v_cvt_pk_bf16_f32 v11, v11, v1
	global_store_short v[50:51], v11, off offset:128
	v_lshlrev_b32_e32 v11, 16, v94
	v_mul_f32_e32 v59, 0xbfb8aa3b, v11
	v_exp_f32_e32 v59, v59
	v_mul_f32_e32 v58, v232, v53
	v_add_f32_e32 v59, 1.0, v59
	v_rcp_f32_e32 v59, v59
	s_nop 0
	v_mul_f32_e32 v11, v59, v11
	v_mul_f32_e32 v11, v11, v58
	v_cvt_pk_bf16_f32 v11, v11, v1
	global_store_short v[50:51], v11, off offset:160
	v_lshlrev_b32_e32 v11, 16, v95
	v_mul_f32_e32 v59, 0xbfb8aa3b, v11
	v_exp_f32_e32 v59, v59
	v_mul_f32_e32 v58, v233, v53
	v_add_f32_e32 v59, 1.0, v59
	v_rcp_f32_e32 v59, v59
	s_nop 0
	v_mul_f32_e32 v11, v59, v11
	v_mul_f32_e32 v11, v11, v58
	v_cvt_pk_bf16_f32 v11, v11, v1
	global_store_short v[50:51], v11, off offset:192
	v_lshlrev_b32_e32 v11, 16, v96
	v_mul_f32_e32 v53, 0xbfb8aa3b, v11
	v_exp_f32_e32 v53, v53
	s_nop 0
	v_add_f32_e32 v53, 1.0, v53
	v_rcp_f32_e32 v53, v53
	s_nop 0
	v_mul_f32_e32 v11, v53, v11
	v_mul_f32_e32 v11, v11, v52
	v_cvt_pk_bf16_f32 v11, v11, v1
	global_store_short v[50:51], v11, off offset:224
	v_add_f32_e32 v11, 0, v79
	v_add_f32_e32 v11, v11, v207
	v_add_f32_e32 v11, v11, v208
	v_add_f32_e32 v11, v11, v85
	v_add_f32_e32 v11, v11, v87
	v_add_f32_e32 v11, v11, v89
	v_add_f32_e32 v11, v11, v91
	v_add_f32_e32 v11, v11, v29
	ds_bpermute_b32 v50, v98, v11
	s_waitcnt lgkmcnt(0)
	v_add_f32_e32 v11, v11, v50
	ds_bpermute_b32 v50, v99, v11
	s_waitcnt lgkmcnt(0)
	v_add_f32_e32 v11, v11, v50
	ds_bpermute_b32 v50, v100, v11
	s_waitcnt lgkmcnt(0)
	v_add_f32_e32 v11, v11, v50
	ds_bpermute_b32 v50, v101, v11
	s_waitcnt lgkmcnt(0)
	v_add_f32_e32 v11, v11, v50
	v_fmac_f32_e32 v207, 0xbc000000, v11
	v_fmac_f32_e32 v79, 0xbc000000, v11
	v_mul_f32_e32 v50, v207, v207
	v_fmac_f32_e32 v50, v79, v79
	v_fmac_f32_e32 v208, 0xbc000000, v11
	v_fmac_f32_e32 v50, v208, v208
	v_fmac_f32_e32 v85, 0xbc000000, v11
	v_fmac_f32_e32 v50, v85, v85
	v_fmac_f32_e32 v87, 0xbc000000, v11
	v_fmac_f32_e32 v50, v87, v87
	v_fmac_f32_e32 v89, 0xbc000000, v11
	v_fmac_f32_e32 v50, v89, v89
	v_fmac_f32_e32 v91, 0xbc000000, v11
	v_fmac_f32_e32 v50, v91, v91
	v_fmac_f32_e32 v29, 0xbc000000, v11
	v_fmac_f32_e32 v50, v29, v29
	ds_bpermute_b32 v11, v98, v50
	s_waitcnt lgkmcnt(0)
	v_add_f32_e32 v11, v50, v11
	ds_bpermute_b32 v50, v99, v11
	s_waitcnt lgkmcnt(0)
	v_add_f32_e32 v11, v11, v50
	ds_bpermute_b32 v50, v100, v11
	s_waitcnt lgkmcnt(0)
	v_add_f32_e32 v11, v11, v50
	ds_bpermute_b32 v50, v101, v11
	s_waitcnt lgkmcnt(0)
	v_add_f32_e32 v11, v11, v50
	v_fmamk_f32 v11, v11, 0x3c000000, v247
	v_cmp_gt_f32_e32 vcc, s77, v11
	v_mul_f32_e32 v50, 0x4f800000, v11
	s_nop 0
	v_cndmask_b32_e32 v11, v11, v50, vcc
	v_sqrt_f32_e32 v50, v11
	s_nop 0
	v_add_u32_e32 v51, -1, v50
	v_fma_f32 v52, -v51, v50, v11
	v_cmp_ge_f32_e64 s[40:41], 0, v52
	v_add_u32_e32 v52, 1, v50
	s_nop 0
	v_cndmask_b32_e64 v51, v50, v51, s[40:41]
	v_fma_f32 v50, -v52, v50, v11
	v_cmp_lt_f32_e64 s[40:41], 0, v50
	s_nop 1
	v_cndmask_b32_e64 v50, v51, v52, s[40:41]
	v_mul_f32_e32 v51, 0x37800000, v50
	v_cndmask_b32_e32 v50, v50, v51, vcc
	v_cmp_class_f32_e32 vcc, v11, v216
	s_nop 1
	v_cndmask_b32_e32 v11, v50, v11, vcc
	v_div_scale_f32 v50, s[4:5], v11, v11, 1.0
	v_rcp_f32_e32 v51, v50
	s_nop 0
	v_fma_f32 v52, -v50, v51, 1.0
	v_fmac_f32_e32 v51, v52, v51
	v_div_scale_f32 v52, vcc, 1.0, v11, 1.0
	v_mul_f32_e32 v53, v52, v51
	v_fma_f32 v58, -v50, v53, v52
	v_fmac_f32_e32 v53, v58, v51
	v_fma_f32 v50, -v50, v53, v52
	v_div_fmas_f32 v50, v50, v51, v53
	v_mul_f32_e32 v51, 0xbfb8aa3b, v37
	v_exp_f32_e32 v51, v51
	v_div_fixup_f32 v11, v50, v11, 1.0
	v_mul_f32_e32 v50, v79, v11
	v_add_f32_e32 v51, 1.0, v51
	v_rcp_f32_e32 v51, v51
	s_nop 0
	v_mul_f32_e32 v37, v51, v37
	v_mul_f32_e32 v37, v37, v50
	v_mul_f32_e32 v50, 0xbfb8aa3b, v36
	v_exp_f32_e32 v50, v50
	v_cvt_pk_bf16_f32 v37, v37, v1
	global_store_short v[8:9], v37, off
	v_mul_f32_e32 v37, v207, v11
	v_add_f32_e32 v50, 1.0, v50
	v_rcp_f32_e32 v50, v50
	s_nop 0
	v_mul_f32_e32 v36, v50, v36
; __device__ __forceinline__ bf16_t f2bf(float x) { return (bf16_t)(cvt_pk_bf16(x, 0.f) & 0xffffu); }
; __device__ __forceinline__ float bf2f(unsigned b) { return __uint_as_float(b << 16); }
; __device__ __forceinline__ float silu_fast(float x) { return x * __builtin_amdgcn_rcpf(1.0f + __expf(-x)); }
; __device__ __forceinline__ void r2_phase(KP p, LAS unsigned char* lds, int G, int bid, int wv) {
;     ...
;         for (int j = 0; j < 4; ++j) {
;             float s = 0.f;
; #pragma unroll
;             for (int i = 0; i < 8; ++i) s += o[i][j];
;             s += __shfl_xor(s, 1); s += __shfl_xor(s, 2); s += __shfl_xor(s, 4); s += __shfl_xor(s, 8);
;             const float mu = s * (1.0f / 128.0f);
;             float q = 0.f;
; #pragma unroll
;             for (int i = 0; i < 8; ++i) { const float d = o[i][j] - mu; q += d * d; }
;             q += __shfl_xor(q, 1); q += __shfl_xor(q, 2); q += __shfl_xor(q, 4); q += __shfl_xor(q, 8);
;             const float rs = 1.0f / sqrtf(q * (1.0f / 128.0f) + 1e-5f);
;             const size_t row = row0 + 16 * wid + 4 * fq + j;
; #pragma unroll
;             for (int i = 0; i < 8; ++i) {
;                 const float gg = bf2f((unsigned)gq[j][i]);
;                 Y[row * DM + h * 128 + 16 * i + fr] = f2bf((o[i][j] - mu) * rs * silu_fast(gg));
;             }
	v_mul_f32_e32 v36, v36, v37
	v_mul_f32_e32 v37, 0xbfb8aa3b, v35
	v_exp_f32_e32 v37, v37
	v_cvt_pk_bf16_f32 v36, v36, v1
	global_store_short v[8:9], v36, off offset:32
	v_mul_f32_e32 v36, v208, v11
	v_add_f32_e32 v37, 1.0, v37
	v_rcp_f32_e32 v37, v37
	s_nop 0
	v_mul_f32_e32 v35, v37, v35
	v_mul_f32_e32 v35, v35, v36
	v_mul_f32_e32 v36, 0xbfb8aa3b, v34
	v_exp_f32_e32 v36, v36
	v_cvt_pk_bf16_f32 v35, v35, v1
	global_store_short v[8:9], v35, off offset:64
	v_mul_f32_e32 v35, v85, v11
	v_add_f32_e32 v36, 1.0, v36
	v_rcp_f32_e32 v36, v36
	s_nop 0
	v_mul_f32_e32 v34, v36, v34
	v_mul_f32_e32 v34, v34, v35
	v_mul_f32_e32 v35, 0xbfb8aa3b, v33
	v_exp_f32_e32 v35, v35
	v_cvt_pk_bf16_f32 v34, v34, v1
	global_store_short v[8:9], v34, off offset:96
	v_mul_f32_e32 v34, v87, v11
	v_add_f32_e32 v35, 1.0, v35
	v_rcp_f32_e32 v35, v35
	s_nop 0
	v_mul_f32_e32 v33, v35, v33
	v_mul_f32_e32 v33, v33, v34
	v_mul_f32_e32 v34, 0xbfb8aa3b, v32
	v_exp_f32_e32 v34, v34
	v_cvt_pk_bf16_f32 v33, v33, v1
	global_store_short v[8:9], v33, off offset:128
	v_mul_f32_e32 v33, v89, v11
	v_add_f32_e32 v34, 1.0, v34
	v_rcp_f32_e32 v34, v34
	s_nop 0
	v_mul_f32_e32 v32, v34, v32
	v_mul_f32_e32 v32, v32, v33
	v_cvt_pk_bf16_f32 v32, v32, v1
	global_store_short v[8:9], v32, off offset:160
	v_mul_f32_e32 v32, v91, v11
	v_mul_f32_e32 v33, 0xbfb8aa3b, v31
	v_mul_f32_e32 v11, v29, v11
	v_mul_f32_e32 v29, 0xbfb8aa3b, v30
	v_exp_f32_e32 v33, v33
	v_exp_f32_e32 v29, v29
	v_add_f32_e32 v33, 1.0, v33
	v_add_f32_e32 v29, 1.0, v29
	v_rcp_f32_e32 v33, v33
	v_rcp_f32_e32 v29, v29
	v_mul_f32_e32 v31, v33, v31
	v_mul_f32_e32 v29, v29, v30
	v_mul_f32_e32 v31, v31, v32
	v_mul_f32_e32 v11, v29, v11
	v_cvt_pk_bf16_f32 v31, v31, v1
	global_store_short v[8:9], v31, off offset:192
	v_cvt_pk_bf16_f32 v11, v11, v1
	global_store_short v[8:9], v11, off offset:224
	v_add_f32_e32 v8, 0, v47
	v_add_f32_e32 v8, v8, v44
	v_add_f32_e32 v8, v8, v45
	v_add_f32_e32 v8, v8, v48
	v_add_f32_e32 v8, v8, v49
	v_add_f32_e32 v8, v8, v81
	v_add_f32_e32 v8, v8, v83
	v_add_f32_e32 v8, v8, v22
	ds_bpermute_b32 v9, v98, v8
	s_waitcnt lgkmcnt(0)
	v_add_f32_e32 v8, v8, v9
	ds_bpermute_b32 v9, v99, v8
	s_waitcnt lgkmcnt(0)
	v_add_f32_e32 v8, v8, v9
	ds_bpermute_b32 v9, v100, v8
	s_waitcnt lgkmcnt(0)
	v_add_f32_e32 v8, v8, v9
	ds_bpermute_b32 v9, v101, v8
	s_waitcnt lgkmcnt(0)
	v_add_f32_e32 v8, v8, v9
	v_fmac_f32_e32 v44, 0xbc000000, v8
	v_fmac_f32_e32 v47, 0xbc000000, v8
	v_mul_f32_e32 v9, v44, v44
	v_fmac_f32_e32 v9, v47, v47
	v_fmac_f32_e32 v45, 0xbc000000, v8
	v_fmac_f32_e32 v9, v45, v45
	v_fmac_f32_e32 v48, 0xbc000000, v8
	v_fmac_f32_e32 v9, v48, v48
	v_fmac_f32_e32 v49, 0xbc000000, v8
	v_fmac_f32_e32 v9, v49, v49
	v_fmac_f32_e32 v81, 0xbc000000, v8
	v_fmac_f32_e32 v9, v81, v81
	v_fmac_f32_e32 v83, 0xbc000000, v8
	v_fmac_f32_e32 v9, v83, v83
	v_fmac_f32_e32 v22, 0xbc000000, v8
	v_fmac_f32_e32 v9, v22, v22
	ds_bpermute_b32 v8, v98, v9
	s_waitcnt lgkmcnt(0)
	v_add_f32_e32 v8, v9, v8
	ds_bpermute_b32 v9, v99, v8
	s_waitcnt lgkmcnt(0)
	v_add_f32_e32 v8, v8, v9
	ds_bpermute_b32 v9, v100, v8
	s_waitcnt lgkmcnt(0)
	v_add_f32_e32 v8, v8, v9
	ds_bpermute_b32 v9, v101, v8
	s_waitcnt lgkmcnt(0)
	v_add_f32_e32 v8, v8, v9
	v_fmamk_f32 v8, v8, 0x3c000000, v247
	v_cmp_gt_f32_e32 vcc, s77, v8
	v_mul_f32_e32 v9, 0x4f800000, v8
	s_nop 0
	v_cndmask_b32_e32 v8, v8, v9, vcc
	v_sqrt_f32_e32 v9, v8
	s_nop 0
	v_add_u32_e32 v11, -1, v9
	v_fma_f32 v29, -v11, v9, v8
	v_cmp_ge_f32_e64 s[40:41], 0, v29
	v_add_u32_e32 v29, 1, v9
	s_nop 0
	v_cndmask_b32_e64 v11, v9, v11, s[40:41]
	v_fma_f32 v9, -v29, v9, v8
	v_cmp_lt_f32_e64 s[40:41], 0, v9
	s_nop 1
	v_cndmask_b32_e64 v9, v11, v29, s[40:41]
	v_mul_f32_e32 v11, 0x37800000, v9
	v_cndmask_b32_e32 v9, v9, v11, vcc
	v_cmp_class_f32_e32 vcc, v8, v216
	s_nop 1
	v_cndmask_b32_e32 v8, v9, v8, vcc
	v_div_scale_f32 v9, s[4:5], v8, v8, 1.0
	v_rcp_f32_e32 v11, v9
	s_nop 0
	v_fma_f32 v29, -v9, v11, 1.0
	v_fmac_f32_e32 v11, v29, v11
	v_div_scale_f32 v29, vcc, 1.0, v8, 1.0
	v_mul_f32_e32 v30, v29, v11
	v_fma_f32 v31, -v9, v30, v29
	v_fmac_f32_e32 v30, v31, v11
	v_fma_f32 v9, -v9, v30, v29
	v_div_fmas_f32 v9, v9, v11, v30
	v_div_fixup_f32 v8, v9, v8, 1.0
	v_lshlrev_b32_e32 v9, 16, v28
	v_mul_f32_e32 v28, 0xbfb8aa3b, v9
	v_exp_f32_e32 v28, v28
	v_mul_f32_e32 v11, v47, v8
	v_add_f32_e32 v28, 1.0, v28
	v_rcp_f32_e32 v28, v28
	s_nop 0
	v_mul_f32_e32 v9, v28, v9
	v_mul_f32_e32 v9, v9, v11
	v_cvt_pk_bf16_f32 v9, v9, v1
	global_store_short v[6:7], v9, off
	v_lshlrev_b32_e32 v9, 16, v27
	v_mul_f32_e32 v27, 0xbfb8aa3b, v9
	v_exp_f32_e32 v27, v27
	v_mul_f32_e32 v11, v44, v8
	v_add_f32_e32 v27, 1.0, v27
	v_rcp_f32_e32 v27, v27
	s_nop 0
	v_mul_f32_e32 v9, v27, v9
	v_mul_f32_e32 v9, v9, v11
	v_cvt_pk_bf16_f32 v9, v9, v1
	global_store_short v[6:7], v9, off offset:32
	v_lshlrev_b32_e32 v9, 16, v26
	v_mul_f32_e32 v26, 0xbfb8aa3b, v9
	v_exp_f32_e32 v26, v26
	v_mul_f32_e32 v11, v45, v8
	v_add_f32_e32 v26, 1.0, v26
	v_rcp_f32_e32 v26, v26
	s_nop 0
	v_mul_f32_e32 v9, v26, v9
	v_mul_f32_e32 v9, v9, v11
	v_cvt_pk_bf16_f32 v9, v9, v1
	global_store_short v[6:7], v9, off offset:64
	v_lshlrev_b32_e32 v9, 16, v25
	v_mul_f32_e32 v25, 0xbfb8aa3b, v9
	v_exp_f32_e32 v25, v25
	v_mul_f32_e32 v11, v48, v8
	v_add_f32_e32 v25, 1.0, v25
	v_rcp_f32_e32 v25, v25
	s_nop 0
	v_mul_f32_e32 v9, v25, v9
	v_mul_f32_e32 v9, v9, v11
	v_cvt_pk_bf16_f32 v9, v9, v1
	global_store_short v[6:7], v9, off offset:96
	v_lshlrev_b32_e32 v9, 16, v24
	v_mul_f32_e32 v24, 0xbfb8aa3b, v9
	v_exp_f32_e32 v24, v24
	v_mul_f32_e32 v11, v49, v8
	v_add_f32_e32 v24, 1.0, v24
	v_rcp_f32_e32 v24, v24
	s_nop 0
	v_mul_f32_e32 v9, v24, v9
	v_mul_f32_e32 v9, v9, v11
	v_cvt_pk_bf16_f32 v9, v9, v1
	global_store_short v[6:7], v9, off offset:128
	v_lshlrev_b32_e32 v9, 16, v23
	v_mul_f32_e32 v23, 0xbfb8aa3b, v9
	v_exp_f32_e32 v23, v23
	v_mul_f32_e32 v11, v81, v8
	v_add_f32_e32 v23, 1.0, v23
	v_rcp_f32_e32 v23, v23
	s_nop 0
	v_mul_f32_e32 v9, v23, v9
	v_mul_f32_e32 v9, v9, v11
	v_cvt_pk_bf16_f32 v9, v9, v1
	global_store_short v[6:7], v9, off offset:160
	v_lshlrev_b32_e32 v9, 16, v21
	v_mul_f32_e32 v21, 0xbfb8aa3b, v9
	v_exp_f32_e32 v21, v21
	v_mul_f32_e32 v11, v83, v8
	v_mul_f32_e32 v8, v22, v8
	v_add_f32_e32 v21, 1.0, v21
	v_rcp_f32_e32 v21, v21
	s_nop 0
	v_mul_f32_e32 v9, v21, v9
	v_mul_f32_e32 v9, v9, v11
	v_cvt_pk_bf16_f32 v9, v9, v1
	global_store_short v[6:7], v9, off offset:192
	v_lshlrev_b32_e32 v9, 16, v19
	v_mul_f32_e32 v11, 0xbfb8aa3b, v9
	v_exp_f32_e32 v11, v11
	s_nop 0
	v_add_f32_e32 v11, 1.0, v11
	v_rcp_f32_e32 v11, v11
	s_nop 0
	v_mul_f32_e32 v9, v11, v9
	v_mul_f32_e32 v8, v9, v8
	v_cvt_pk_bf16_f32 v8, v8, v1
	global_store_short v[6:7], v8, off offset:224
	v_add_f32_e32 v6, 0, v46
	v_add_f32_e32 v6, v6, v42
	v_add_f32_e32 v6, v6, v38
	v_add_f32_e32 v6, v6, v39
	v_add_f32_e32 v6, v6, v40
	v_add_f32_e32 v6, v6, v41
	v_add_f32_e32 v6, v6, v43
	v_add_f32_e32 v6, v6, v20
	ds_bpermute_b32 v7, v98, v6
	s_waitcnt lgkmcnt(0)
; __device__ __forceinline__ bf16_t f2bf(float x) { return (bf16_t)(cvt_pk_bf16(x, 0.f) & 0xffffu); }
; __device__ __forceinline__ float bf2f(unsigned b) { return __uint_as_float(b << 16); }
; __device__ __forceinline__ float silu_fast(float x) { return x * __builtin_amdgcn_rcpf(1.0f + __expf(-x)); }
; __device__ __forceinline__ void r2_phase(KP p, LAS unsigned char* lds, int G, int bid, int wv) {
;     ...
;         for (int j = 0; j < 4; ++j) {
;             float s = 0.f;
; #pragma unroll
;             for (int i = 0; i < 8; ++i) s += o[i][j];
;             s += __shfl_xor(s, 1); s += __shfl_xor(s, 2); s += __shfl_xor(s, 4); s += __shfl_xor(s, 8);
;             const float mu = s * (1.0f / 128.0f);
;             float q = 0.f;
; #pragma unroll
;             for (int i = 0; i < 8; ++i) { const float d = o[i][j] - mu; q += d * d; }
;             q += __shfl_xor(q, 1); q += __shfl_xor(q, 2); q += __shfl_xor(q, 4); q += __shfl_xor(q, 8);
;             const float rs = 1.0f / sqrtf(q * (1.0f / 128.0f) + 1e-5f);
;             const size_t row = row0 + 16 * wid + 4 * fq + j;
; #pragma unroll
;             for (int i = 0; i < 8; ++i) {
;                 const float gg = bf2f((unsigned)gq[j][i]);
;                 Y[row * DM + h * 128 + 16 * i + fr] = f2bf((o[i][j] - mu) * rs * silu_fast(gg));
;             }
;         }
;         __syncthreads();
	v_add_f32_e32 v6, v6, v7
	ds_bpermute_b32 v7, v99, v6
	s_waitcnt lgkmcnt(0)
	v_add_f32_e32 v6, v6, v7
	ds_bpermute_b32 v7, v100, v6
	s_waitcnt lgkmcnt(0)
	v_add_f32_e32 v6, v6, v7
	ds_bpermute_b32 v7, v101, v6
	s_waitcnt lgkmcnt(0)
	v_add_f32_e32 v6, v6, v7
	v_fmac_f32_e32 v42, 0xbc000000, v6
	v_fmac_f32_e32 v46, 0xbc000000, v6
	v_mul_f32_e32 v7, v42, v42
	v_fmac_f32_e32 v7, v46, v46
	v_fmac_f32_e32 v38, 0xbc000000, v6
	v_fmac_f32_e32 v7, v38, v38
	v_fmac_f32_e32 v39, 0xbc000000, v6
	v_fmac_f32_e32 v7, v39, v39
	v_fmac_f32_e32 v40, 0xbc000000, v6
	v_fmac_f32_e32 v7, v40, v40
	v_fmac_f32_e32 v41, 0xbc000000, v6
	v_fmac_f32_e32 v7, v41, v41
	v_fmac_f32_e32 v43, 0xbc000000, v6
	v_fmac_f32_e32 v7, v43, v43
	v_fmac_f32_e32 v20, 0xbc000000, v6
	v_fmac_f32_e32 v7, v20, v20
	ds_bpermute_b32 v6, v98, v7
	s_waitcnt lgkmcnt(0)
	v_add_f32_e32 v6, v7, v6
	ds_bpermute_b32 v7, v99, v6
	s_waitcnt lgkmcnt(0)
	v_add_f32_e32 v6, v6, v7
	ds_bpermute_b32 v7, v100, v6
	s_waitcnt lgkmcnt(0)
	v_add_f32_e32 v6, v6, v7
	ds_bpermute_b32 v7, v101, v6
	s_waitcnt lgkmcnt(0)
	v_add_f32_e32 v6, v6, v7
	v_fmamk_f32 v6, v6, 0x3c000000, v247
	v_cmp_gt_f32_e32 vcc, s77, v6
	v_mul_f32_e32 v7, 0x4f800000, v6
	s_nop 0
	v_cndmask_b32_e32 v6, v6, v7, vcc
	v_sqrt_f32_e32 v7, v6
	s_nop 0
	v_add_u32_e32 v8, -1, v7
	v_fma_f32 v9, -v8, v7, v6
	v_cmp_ge_f32_e64 s[40:41], 0, v9
	v_add_u32_e32 v9, 1, v7
	s_nop 0
	v_cndmask_b32_e64 v8, v7, v8, s[40:41]
	v_fma_f32 v7, -v9, v7, v6
	v_cmp_lt_f32_e64 s[40:41], 0, v7
	s_nop 1
	v_cndmask_b32_e64 v7, v8, v9, s[40:41]
	v_mul_f32_e32 v8, 0x37800000, v7
	v_cndmask_b32_e32 v7, v7, v8, vcc
	v_cmp_class_f32_e32 vcc, v6, v216
	s_nop 1
	v_cndmask_b32_e32 v6, v7, v6, vcc
	v_div_scale_f32 v7, s[4:5], v6, v6, 1.0
	v_rcp_f32_e32 v8, v7
	s_nop 0
	v_fma_f32 v9, -v7, v8, 1.0
	v_fmac_f32_e32 v8, v9, v8
	v_div_scale_f32 v9, vcc, 1.0, v6, 1.0
	v_mul_f32_e32 v11, v9, v8
	v_fma_f32 v19, -v7, v11, v9
	v_fmac_f32_e32 v11, v19, v8
	v_fma_f32 v7, -v7, v11, v9
	v_div_fmas_f32 v7, v7, v8, v11
	v_div_fixup_f32 v6, v7, v6, 1.0
	v_mul_f32_e32 v7, 0xbfb8aa3b, v4
	v_exp_f32_e32 v7, v7
	v_mul_f32_e32 v5, v46, v6
	v_add_f32_e32 v7, 1.0, v7
	v_rcp_f32_e32 v7, v7
	s_nop 0
	v_mul_f32_e32 v4, v7, v4
	v_mul_f32_e32 v4, v4, v5
	v_cvt_pk_bf16_f32 v4, v4, v1
	global_store_short v[2:3], v4, off
	s_waitcnt vmcnt(31)
	v_lshlrev_b32_e32 v4, 16, v17
	v_mul_f32_e32 v7, 0xbfb8aa3b, v4
	v_exp_f32_e32 v7, v7
	v_mul_f32_e32 v5, v42, v6
	v_add_f32_e32 v7, 1.0, v7
	v_rcp_f32_e32 v7, v7
	s_nop 0
	v_mul_f32_e32 v4, v7, v4
	v_mul_f32_e32 v4, v4, v5
	v_cvt_pk_bf16_f32 v4, v4, v1
	global_store_short v[2:3], v4, off offset:32
	s_waitcnt vmcnt(31)
	v_lshlrev_b32_e32 v4, 16, v16
	v_mul_f32_e32 v7, 0xbfb8aa3b, v4
	v_exp_f32_e32 v7, v7
	v_mul_f32_e32 v5, v38, v6
	v_add_f32_e32 v7, 1.0, v7
	v_rcp_f32_e32 v7, v7
	s_nop 0
	v_mul_f32_e32 v4, v7, v4
	v_mul_f32_e32 v4, v4, v5
	v_cvt_pk_bf16_f32 v4, v4, v1
	global_store_short v[2:3], v4, off offset:64
	s_waitcnt vmcnt(31)
	v_lshlrev_b32_e32 v4, 16, v15
	v_mul_f32_e32 v7, 0xbfb8aa3b, v4
	v_exp_f32_e32 v7, v7
	v_mul_f32_e32 v5, v39, v6
	v_add_f32_e32 v7, 1.0, v7
	v_rcp_f32_e32 v7, v7
	s_nop 0
	v_mul_f32_e32 v4, v7, v4
	v_mul_f32_e32 v4, v4, v5
	v_cvt_pk_bf16_f32 v4, v4, v1
	global_store_short v[2:3], v4, off offset:96
	s_waitcnt vmcnt(31)
	v_lshlrev_b32_e32 v4, 16, v14
	v_mul_f32_e32 v7, 0xbfb8aa3b, v4
	v_exp_f32_e32 v7, v7
	v_mul_f32_e32 v5, v40, v6
	v_add_f32_e32 v7, 1.0, v7
	v_rcp_f32_e32 v7, v7
	s_nop 0
	v_mul_f32_e32 v4, v7, v4
	v_mul_f32_e32 v4, v4, v5
	v_cvt_pk_bf16_f32 v4, v4, v1
	global_store_short v[2:3], v4, off offset:128
	s_waitcnt vmcnt(31)
	v_lshlrev_b32_e32 v4, 16, v13
	v_mul_f32_e32 v7, 0xbfb8aa3b, v4
	v_exp_f32_e32 v7, v7
	v_mul_f32_e32 v5, v41, v6
	v_add_f32_e32 v7, 1.0, v7
	v_rcp_f32_e32 v7, v7
	s_nop 0
	v_mul_f32_e32 v4, v7, v4
	v_mul_f32_e32 v4, v4, v5
	v_cvt_pk_bf16_f32 v4, v4, v1
	global_store_short v[2:3], v4, off offset:160
	s_waitcnt vmcnt(31)
	v_lshlrev_b32_e32 v4, 16, v12
	v_mul_f32_e32 v7, 0xbfb8aa3b, v4
	v_exp_f32_e32 v7, v7
	v_mul_f32_e32 v5, v43, v6
	v_add_f32_e32 v7, 1.0, v7
	v_rcp_f32_e32 v7, v7
	s_nop 0
	v_mul_f32_e32 v4, v7, v4
	v_mul_f32_e32 v4, v4, v5
	v_cvt_pk_bf16_f32 v4, v4, v1
	global_store_short v[2:3], v4, off offset:192
	s_waitcnt vmcnt(31)
	v_lshlrev_b32_e32 v4, 16, v10
	v_mul_f32_e32 v5, v20, v6
	v_mul_f32_e32 v6, 0xbfb8aa3b, v4
	v_exp_f32_e32 v6, v6
	s_nop 0
	v_add_f32_e32 v6, 1.0, v6
	v_rcp_f32_e32 v6, v6
	s_nop 0
	v_mul_f32_e32 v4, v6, v4
	v_mul_f32_e32 v4, v4, v5
	v_cvt_pk_bf16_f32 v4, v4, v1
	global_store_short v[2:3], v4, off offset:224
	s_barrier
	s_cbranch_scc0 .LBB0_107
	v_readlane_b32 s36, v253, 39
	v_readlane_b32 s26, v254, 35
	v_readlane_b32 s10, v254, 37
	s_movk_i32 s41, 0x2000
	s_mov_b32 s35, 0x3f2aaaab
	s_mov_b32 s40, 0xf800000
	s_mov_b32 s28, 0x20000
	v_readlane_b32 s37, v253, 40
	s_movk_i32 s77, 0x71
	v_readlane_b32 s86, v253, 41
	v_readlane_b32 s27, v254, 36
	v_readlane_b32 s11, v254, 38

; __device__ __forceinline__ void norm_phase(const float* src_lat, const float* src_ctx, int nrows, const float* gnorm, const float* shift, const float* scale, ...
;     ...
;     for (int row = bid * 8 + wid; row < nrows; row += G * 8) {
;         const float* xp = row < MLAT ? src_lat + (size_t)row * DM : src_ctx + (size_t)(row - MLAT) * DM;
;         const int r = row < MLAT ? (row >> 11) : 4;
;         f32x4 v[8], gg[8], sh[8], sl[8];
; #pragma unroll
;         for (int i = 0; i < 8; ++i) v[i] = *(const f32x4*)(xp + 4 * (lane + 64 * i));
;         if (mode != 2) {
; #pragma unroll
;             for (int i = 0; i < 8; ++i) { const int c = 4 * (lane + 64 * i); gg[i] = *(const f32x4*)(gnorm + c);
;                 if (mode == 0) { sh[i] = *(const f32x4*)(shift + (size_t)r * NMODC + c); sl[i] = *(const f32x4*)(scale + (size_t)r * NMODC + c); } }
;         }
;         if (parts && row >= MLAT) {
; #pragma unroll
;             for (int i = 0; i < 8; ++i) { const size_t o = (size_t)(row - MLAT) * DM + 4 * (lane + 64 * i);
;                 const f32x4 ps = (*(const f32x4*)(parts + o) + *(const f32x4*)(parts + (size_t)MCTX * DM + o)) + (*(const f32x4*)(parts + (size_t)2 * MCTX * DM + o) + *(const f32x4*)(parts + (size_t)3 * MCTX * DM + o));
;                 v[i] = v[i] + ps * (*(const f32x4*)(pgate + 4 * (lane + 64 * i)) * 0.5f); }
.LBB0_565:
	v_add_u32_e32 v0, 0xffffe000, v198
	v_cmp_gt_i32_e32 vcc, s41, v198
	v_mov_b32_e32 v4, s7
	v_mov_b32_e32 v5, s85
	v_cndmask_b32_e32 v3, 0, v199, vcc
	v_cndmask_b32_e32 v2, v0, v198, vcc
	v_cndmask_b32_e32 v5, v4, v5, vcc
	v_mov_b32_e32 v4, s6
	v_mov_b32_e32 v6, s84
	v_cndmask_b32_e32 v4, v4, v6, vcc
	v_lshlrev_b64 v[2:3], 13, v[2:3]
	v_min_i32_e32 v16, 0x2000, v198
	v_lshl_add_u64 v[2:3], v[4:5], 0, v[2:3]
	v_lshlrev_b32_e32 v14, 2, v134
	v_mov_b32_e32 v15, v1
	v_ashrrev_i32_e32 v16, 11, v16
	v_lshl_add_u64 v[4:5], v[2:3], 0, v[14:15]
	v_mov_b32_e32 v203, v1
	v_mul_hi_i32_i24_e32 v17, 0x4800, v16
	v_mul_i32_i24_e32 v16, 0x4800, v16
	global_load_dwordx4 v[106:109], v[4:5], off
	global_load_dwordx4 v[86:89], v[4:5], off offset:1024
	global_load_dwordx4 v[70:73], v[4:5], off offset:2048
	global_load_dwordx4 v[54:57], v[4:5], off offset:3072
	v_lshl_add_u64 v[4:5], v[2:3], 0, v[202:203]
	v_mov_b32_e32 v205, v1
	v_mov_b32_e32 v207, v1
	v_mov_b32_e32 v209, v1
	v_lshlrev_b64 v[16:17], 2, v[16:17]
	v_lshl_add_u64 v[6:7], v[2:3], 0, v[204:205]
	global_load_dwordx4 v[34:37], v[4:5], off
	global_load_dwordx4 v[10:13], v[6:7], off
	v_lshl_add_u64 v[4:5], v[2:3], 0, v[206:207]
	v_lshl_add_u64 v[2:3], v[2:3], 0, v[208:209]
	v_lshl_add_u64 v[22:23], s[10:11], 0, v[16:17]
	v_lshl_add_u64 v[16:17], s[12:13], 0, v[16:17]
	global_load_dwordx4 v[6:9], v[4:5], off
	s_nop 0
	global_load_dwordx4 v[2:5], v[2:3], off
	v_lshl_add_u64 v[18:19], v[22:23], 0, v[14:15]
	v_lshl_add_u64 v[14:15], v[16:17], 0, v[14:15]
	global_load_dwordx4 v[122:125], v[150:151], off
	global_load_dwordx4 v[110:113], v[150:151], off offset:1024
	global_load_dwordx4 v[118:121], v[18:19], off
	global_load_dwordx4 v[102:105], v[18:19], off offset:1024
	global_load_dwordx4 v[126:129], v[14:15], off
	global_load_dwordx4 v[114:117], v[14:15], off offset:1024
	global_load_dwordx4 v[94:97], v[150:151], off offset:2048
	global_load_dwordx4 v[78:81], v[150:151], off offset:3072
	global_load_dwordx4 v[90:93], v[18:19], off offset:2048
	global_load_dwordx4 v[74:77], v[18:19], off offset:3072
	global_load_dwordx4 v[98:101], v[14:15], off offset:2048
	global_load_dwordx4 v[82:85], v[14:15], off offset:3072
	v_lshl_add_u64 v[14:15], v[22:23], 0, v[202:203]
	v_lshl_add_u64 v[18:19], v[16:17], 0, v[202:203]
	global_load_dwordx4 v[58:61], v[14:15], off
	global_load_dwordx4 v[62:65], v[18:19], off
	global_load_dwordx4 v[66:69], v[152:153], off
	global_load_dwordx4 v[46:49], v[154:155], off
	v_lshl_add_u64 v[14:15], v[22:23], 0, v[204:205]
	v_lshl_add_u64 v[18:19], v[16:17], 0, v[204:205]
	global_load_dwordx4 v[42:45], v[14:15], off
	global_load_dwordx4 v[50:53], v[18:19], off
	v_lshl_add_u64 v[14:15], v[22:23], 0, v[206:207]
	v_lshl_add_u64 v[18:19], v[16:17], 0, v[206:207]
	global_load_dwordx4 v[26:29], v[14:15], off
	global_load_dwordx4 v[30:33], v[18:19], off
	global_load_dwordx4 v[38:41], v[156:157], off
	s_nop 0
	global_load_dwordx4 v[18:21], v[158:159], off
	v_lshl_add_u64 v[14:15], v[22:23], 0, v[208:209]
	v_lshl_add_u64 v[22:23], v[16:17], 0, v[208:209]
	global_load_dwordx4 v[14:17], v[14:15], off
	s_nop 0
	global_load_dwordx4 v[22:25], v[22:23], off
	v_cmp_lt_i32_e32 vcc, s94, v198
	s_and_b64 s[24:25], s[4:5], vcc
	s_and_saveexec_b64 s[2:3], s[24:25]
	s_cbranch_execz .LBB0_564
	v_lshlrev_b64 v[130:131], 11, v[0:1]
	v_or_b32_e32 v132, v130, v134
	v_mov_b32_e32 v133, v131
	v_lshlrev_b64 v[218:219], 2, v[132:133]
	s_mov_b64 s[98:99], 0x1000
	v_lshl_add_u64 v[132:133], s[14:15], 0, v[218:219]
	v_lshl_add_u64 v[176:177], s[16:17], 0, v[218:219]
	v_lshl_add_u64 v[180:181], s[18:19], 0, v[218:219]
	v_lshl_add_u64 v[218:219], s[20:21], 0, v[218:219]
	global_load_dwordx4 v[210:213], v[132:133], off
	global_load_dwordx4 v[224:227], v[176:177], off
	global_load_dwordx4 v[164:167], v[180:181], off
	global_load_dwordx4 v[168:171], v[218:219], off
	global_load_dwordx4 v[172:175], v[160:161], off
	s_waitcnt vmcnt(0)
	v_pk_add_f32 v[230:231], v[210:211], v[224:225]
	v_pk_add_f32 v[228:229], v[212:213], v[226:227]
	v_pk_add_f32 v[166:167], v[166:167], v[170:171]
	v_pk_add_f32 v[164:165], v[164:165], v[168:169]
	v_pk_add_f32 v[228:229], v[228:229], v[166:167]
	v_pk_add_f32 v[230:231], v[230:231], v[164:165]
	v_pk_mul_f32 v[174:175], v[174:175], 0.5 op_sel_hi:[1,0]
	v_pk_mul_f32 v[172:173], v[172:173], 0.5 op_sel_hi:[1,0]
	s_nop 0
	v_pk_fma_f32 v[108:109], v[228:229], v[174:175], v[108:109]
	v_pk_fma_f32 v[106:107], v[230:231], v[172:173], v[106:107]
	global_load_dwordx4 v[210:213], v[132:133], off offset:1024
	global_load_dwordx4 v[224:227], v[176:177], off offset:1024
	global_load_dwordx4 v[164:167], v[180:181], off offset:1024
	global_load_dwordx4 v[168:171], v[218:219], off offset:1024
	global_load_dwordx4 v[172:175], v[184:185], off
	s_waitcnt vmcnt(0)
	v_pk_add_f32 v[230:231], v[210:211], v[224:225]
	v_pk_add_f32 v[228:229], v[212:213], v[226:227]
	v_pk_add_f32 v[166:167], v[166:167], v[170:171]
	v_pk_add_f32 v[164:165], v[164:165], v[168:169]
	v_pk_add_f32 v[228:229], v[228:229], v[166:167]
	v_pk_add_f32 v[230:231], v[230:231], v[164:165]
	v_pk_mul_f32 v[174:175], v[174:175], 0.5 op_sel_hi:[1,0]
	v_pk_mul_f32 v[172:173], v[172:173], 0.5 op_sel_hi:[1,0]
	s_nop 0
	v_pk_fma_f32 v[88:89], v[228:229], v[174:175], v[88:89]
	v_pk_fma_f32 v[86:87], v[230:231], v[172:173], v[86:87]
	global_load_dwordx4 v[210:213], v[132:133], off offset:2048
	global_load_dwordx4 v[224:227], v[176:177], off offset:2048
	global_load_dwordx4 v[164:167], v[180:181], off offset:2048
	global_load_dwordx4 v[168:171], v[218:219], off offset:2048
	global_load_dwordx4 v[172:175], v[186:187], off
	s_waitcnt vmcnt(0)
; __device__ __forceinline__ void norm_phase(const float* src_lat, const float* src_ctx, int nrows, const float* gnorm, const float* shift, const float* scale, ...
;     ...
;         if (parts && row >= MLAT) {
; #pragma unroll
;             for (int i = 0; i < 8; ++i) { const size_t o = (size_t)(row - MLAT) * DM + 4 * (lane + 64 * i);
;                 const f32x4 ps = (*(const f32x4*)(parts + o) + *(const f32x4*)(parts + (size_t)MCTX * DM + o)) + (*(const f32x4*)(parts + (size_t)2 * MCTX * DM + o) + *(const f32x4*)(parts + (size_t)3 * MCTX * DM + o));
;                 v[i] = v[i] + ps * (*(const f32x4*)(pgate + 4 * (lane + 64 * i)) * 0.5f); }
;         }
	v_pk_add_f32 v[230:231], v[210:211], v[224:225]
	v_pk_add_f32 v[228:229], v[212:213], v[226:227]
	v_pk_add_f32 v[166:167], v[166:167], v[170:171]
	v_pk_add_f32 v[164:165], v[164:165], v[168:169]
	v_pk_add_f32 v[228:229], v[228:229], v[166:167]
	v_pk_add_f32 v[230:231], v[230:231], v[164:165]
	v_pk_mul_f32 v[174:175], v[174:175], 0.5 op_sel_hi:[1,0]
	v_pk_mul_f32 v[172:173], v[172:173], 0.5 op_sel_hi:[1,0]
	s_nop 0
	v_pk_fma_f32 v[72:73], v[228:229], v[174:175], v[72:73]
	v_pk_fma_f32 v[70:71], v[230:231], v[172:173], v[70:71]
	global_load_dwordx4 v[210:213], v[132:133], off offset:3072
	global_load_dwordx4 v[224:227], v[176:177], off offset:3072
	global_load_dwordx4 v[164:167], v[180:181], off offset:3072
	global_load_dwordx4 v[168:171], v[218:219], off offset:3072
	global_load_dwordx4 v[172:175], v[188:189], off
	s_waitcnt vmcnt(0)
	v_pk_add_f32 v[230:231], v[210:211], v[224:225]
	v_pk_add_f32 v[228:229], v[212:213], v[226:227]
	v_pk_add_f32 v[166:167], v[166:167], v[170:171]
	v_pk_add_f32 v[164:165], v[164:165], v[168:169]
	v_pk_add_f32 v[228:229], v[228:229], v[166:167]
	v_pk_add_f32 v[230:231], v[230:231], v[164:165]
	v_pk_mul_f32 v[174:175], v[174:175], 0.5 op_sel_hi:[1,0]
	v_pk_mul_f32 v[172:173], v[172:173], 0.5 op_sel_hi:[1,0]
	s_nop 0
	v_pk_fma_f32 v[56:57], v[228:229], v[174:175], v[56:57]
	v_pk_fma_f32 v[54:55], v[230:231], v[172:173], v[54:55]
	v_lshl_add_u64 v[132:133], v[132:133], 0, s[98:99]
	v_lshl_add_u64 v[176:177], v[176:177], 0, s[98:99]
	v_lshl_add_u64 v[180:181], v[180:181], 0, s[98:99]
	v_lshl_add_u64 v[218:219], v[218:219], 0, s[98:99]
	global_load_dwordx4 v[210:213], v[132:133], off
	global_load_dwordx4 v[224:227], v[176:177], off
	global_load_dwordx4 v[164:167], v[180:181], off
	global_load_dwordx4 v[168:171], v[218:219], off
	global_load_dwordx4 v[172:175], v[190:191], off
	s_waitcnt vmcnt(0)
	v_pk_add_f32 v[230:231], v[210:211], v[224:225]
	v_pk_add_f32 v[228:229], v[212:213], v[226:227]
	v_pk_add_f32 v[166:167], v[166:167], v[170:171]
	v_pk_add_f32 v[164:165], v[164:165], v[168:169]
	v_pk_add_f32 v[228:229], v[228:229], v[166:167]
	v_pk_add_f32 v[230:231], v[230:231], v[164:165]
	v_pk_mul_f32 v[174:175], v[174:175], 0.5 op_sel_hi:[1,0]
	v_pk_mul_f32 v[172:173], v[172:173], 0.5 op_sel_hi:[1,0]
	s_nop 0
	v_pk_fma_f32 v[36:37], v[228:229], v[174:175], v[36:37]
	v_pk_fma_f32 v[34:35], v[230:231], v[172:173], v[34:35]
	global_load_dwordx4 v[210:213], v[132:133], off offset:1024
	global_load_dwordx4 v[224:227], v[176:177], off offset:1024
	global_load_dwordx4 v[164:167], v[180:181], off offset:1024
	global_load_dwordx4 v[168:171], v[218:219], off offset:1024
	global_load_dwordx4 v[172:175], v[192:193], off
	s_waitcnt vmcnt(0)
	v_pk_add_f32 v[230:231], v[210:211], v[224:225]
	v_pk_add_f32 v[228:229], v[212:213], v[226:227]
	v_pk_add_f32 v[166:167], v[166:167], v[170:171]
	v_pk_add_f32 v[164:165], v[164:165], v[168:169]
	v_pk_add_f32 v[228:229], v[228:229], v[166:167]
	v_pk_add_f32 v[230:231], v[230:231], v[164:165]
	v_pk_mul_f32 v[174:175], v[174:175], 0.5 op_sel_hi:[1,0]
	v_pk_mul_f32 v[172:173], v[172:173], 0.5 op_sel_hi:[1,0]
	s_nop 0
	v_pk_fma_f32 v[12:13], v[228:229], v[174:175], v[12:13]
	v_pk_fma_f32 v[10:11], v[230:231], v[172:173], v[10:11]
	global_load_dwordx4 v[210:213], v[132:133], off offset:2048
	global_load_dwordx4 v[224:227], v[176:177], off offset:2048
	global_load_dwordx4 v[164:167], v[180:181], off offset:2048
	global_load_dwordx4 v[168:171], v[218:219], off offset:2048
	global_load_dwordx4 v[172:175], v[194:195], off
	s_waitcnt vmcnt(0)
	v_pk_add_f32 v[230:231], v[210:211], v[224:225]
	v_pk_add_f32 v[228:229], v[212:213], v[226:227]
	v_pk_add_f32 v[166:167], v[166:167], v[170:171]
	v_pk_add_f32 v[164:165], v[164:165], v[168:169]
	v_pk_add_f32 v[228:229], v[228:229], v[166:167]
	v_pk_add_f32 v[230:231], v[230:231], v[164:165]
	v_pk_mul_f32 v[174:175], v[174:175], 0.5 op_sel_hi:[1,0]
	v_pk_mul_f32 v[172:173], v[172:173], 0.5 op_sel_hi:[1,0]
	s_nop 0
	v_pk_fma_f32 v[8:9], v[228:229], v[174:175], v[8:9]
	v_pk_fma_f32 v[6:7], v[230:231], v[172:173], v[6:7]
	global_load_dwordx4 v[210:213], v[132:133], off offset:3072
	global_load_dwordx4 v[224:227], v[176:177], off offset:3072
	global_load_dwordx4 v[164:167], v[180:181], off offset:3072
	global_load_dwordx4 v[168:171], v[218:219], off offset:3072
	global_load_dwordx4 v[172:175], v[196:197], off
	s_waitcnt vmcnt(0)
	v_pk_add_f32 v[230:231], v[210:211], v[224:225]
	v_pk_add_f32 v[228:229], v[212:213], v[226:227]
	v_pk_add_f32 v[166:167], v[166:167], v[170:171]
	v_pk_add_f32 v[164:165], v[164:165], v[168:169]
	v_pk_add_f32 v[228:229], v[228:229], v[166:167]
	v_pk_add_f32 v[230:231], v[230:231], v[164:165]
	v_pk_mul_f32 v[174:175], v[174:175], 0.5 op_sel_hi:[1,0]
	v_pk_mul_f32 v[172:173], v[172:173], 0.5 op_sel_hi:[1,0]
	s_nop 0
	v_pk_fma_f32 v[4:5], v[228:229], v[174:175], v[4:5]
	v_pk_fma_f32 v[2:3], v[230:231], v[172:173], v[2:3]
	s_branch .LBB0_564
